# nt hints also on the f32 weight loads of the GEMM-tail transposers (GU1, D1, WIN, PAPR tails) and on the window-copy loads
# baseline (speedup 1.0000x reference)
.LBB0_406:
	s_lshl_b32 s26, s15, 1
	s_lshl_b32 s27, s14, 1
	v_or_b32_e32 v9, s26, v1
	v_or_b32_e32 v11, s27, v0
	s_add_i32 s28, s26, 4
	s_add_i32 s29, s27, 4
	s_add_i32 s30, s26, 8
	s_add_i32 s31, s27, 8
	s_add_i32 s33, s26, 12
	s_add_i32 s35, s27, 12
	s_add_i32 s52, s26, 16
	s_add_i32 s53, s27, 16
	s_add_i32 s54, s26, 20
	s_add_i32 s55, s27, 20
	s_add_i32 s56, s26, 24
	s_add_i32 s57, s27, 24
	s_add_i32 s26, s26, 28
	s_add_i32 s27, s27, 28
	v_add_u32_e32 v22, v11, v10
	v_or_b32_e32 v52, s28, v1
	v_or_b32_e32 v53, s29, v0
	v_or_b32_e32 v54, s30, v1
	v_or_b32_e32 v55, s31, v0
	v_or_b32_e32 v56, s33, v1
	v_or_b32_e32 v57, s35, v0
	v_or_b32_e32 v58, s52, v1
	v_or_b32_e32 v59, s53, v0
	v_or_b32_e32 v60, s54, v1
	v_or_b32_e32 v61, s55, v0
	v_or_b32_e32 v62, s56, v1
	v_or_b32_e32 v63, s57, v0
	v_or_b32_e32 v64, s26, v1
	v_or_b32_e32 v65, s27, v0
	v_add_u32_e32 v20, v9, v3
	v_ashrrev_i32_e32 v23, 31, v22
	v_add_u32_e32 v24, v52, v3
	v_add_u32_e32 v26, v53, v10
	v_add_u32_e32 v28, v54, v3
	v_add_u32_e32 v30, v55, v10
	v_add_u32_e32 v32, v56, v3
	v_add_u32_e32 v34, v57, v10
	v_add_u32_e32 v36, v58, v3
	v_add_u32_e32 v38, v59, v10
	v_add_u32_e32 v40, v60, v3
	v_add_u32_e32 v42, v61, v10
	v_add_u32_e32 v44, v62, v3
	v_add_u32_e32 v46, v63, v10
	v_add_u32_e32 v48, v64, v3
	v_add_u32_e32 v50, v65, v10
	v_ashrrev_i32_e32 v21, 31, v20
	v_lshlrev_b64 v[22:23], 13, v[22:23]
	v_ashrrev_i32_e32 v27, 31, v26
	v_ashrrev_i32_e32 v25, 31, v24
	v_ashrrev_i32_e32 v31, 31, v30
	v_ashrrev_i32_e32 v29, 31, v28
	v_ashrrev_i32_e32 v35, 31, v34
	v_ashrrev_i32_e32 v33, 31, v32
	v_ashrrev_i32_e32 v39, 31, v38
	v_ashrrev_i32_e32 v37, 31, v36
	v_ashrrev_i32_e32 v43, 31, v42
	v_ashrrev_i32_e32 v41, 31, v40
	v_ashrrev_i32_e32 v47, 31, v46
	v_ashrrev_i32_e32 v45, 31, v44
	v_ashrrev_i32_e32 v51, 31, v50
	v_ashrrev_i32_e32 v49, 31, v48
	v_lshlrev_b64 v[20:21], 13, v[20:21]
	v_lshl_add_u64 v[22:23], v[12:13], 0, v[22:23]
	v_lshlrev_b64 v[24:25], 13, v[24:25]
	v_lshlrev_b64 v[26:27], 13, v[26:27]
	v_lshlrev_b64 v[28:29], 13, v[28:29]
	v_lshlrev_b64 v[30:31], 13, v[30:31]
	v_lshlrev_b64 v[32:33], 13, v[32:33]
	v_lshlrev_b64 v[34:35], 13, v[34:35]
	v_lshlrev_b64 v[36:37], 13, v[36:37]
	v_lshlrev_b64 v[38:39], 13, v[38:39]
	v_lshlrev_b64 v[40:41], 13, v[40:41]
	v_lshlrev_b64 v[42:43], 13, v[42:43]
	v_lshlrev_b64 v[44:45], 13, v[44:45]
	v_lshlrev_b64 v[46:47], 13, v[46:47]
	v_lshlrev_b64 v[48:49], 13, v[48:49]
	v_lshlrev_b64 v[50:51], 13, v[50:51]
	v_lshl_add_u64 v[20:21], v[12:13], 0, v[20:21]
	v_lshl_add_u64 v[26:27], v[12:13], 0, v[26:27]
	v_lshl_add_u64 v[24:25], v[12:13], 0, v[24:25]
	v_lshl_add_u64 v[30:31], v[12:13], 0, v[30:31]
	v_lshl_add_u64 v[28:29], v[12:13], 0, v[28:29]
	v_lshl_add_u64 v[34:35], v[12:13], 0, v[34:35]
	v_lshl_add_u64 v[32:33], v[12:13], 0, v[32:33]
	v_lshl_add_u64 v[38:39], v[12:13], 0, v[38:39]
	v_lshl_add_u64 v[36:37], v[12:13], 0, v[36:37]
	v_lshl_add_u64 v[42:43], v[12:13], 0, v[42:43]
	v_lshl_add_u64 v[40:41], v[12:13], 0, v[40:41]
	v_lshl_add_u64 v[46:47], v[12:13], 0, v[46:47]
	v_lshl_add_u64 v[44:45], v[12:13], 0, v[44:45]
	v_lshl_add_u64 v[50:51], v[12:13], 0, v[50:51]
	v_lshl_add_u64 v[48:49], v[12:13], 0, v[48:49]
	global_load_dword v66, v[22:23], off nt
	global_load_dword v67, v[20:21], off nt
	global_load_dword v68, v[26:27], off nt
	global_load_dword v69, v[24:25], off nt
	global_load_dword v70, v[30:31], off nt
	global_load_dword v71, v[28:29], off nt
	global_load_dword v72, v[34:35], off nt
	global_load_dword v73, v[32:33], off nt
	global_load_dword v74, v[38:39], off nt
	global_load_dword v75, v[36:37], off nt
	global_load_dword v76, v[42:43], off nt
	global_load_dword v77, v[40:41], off nt
	global_load_dword v78, v[46:47], off nt
	global_load_dword v79, v[44:45], off nt
	global_load_dword v80, v[50:51], off nt
	global_load_dword v81, v[48:49], off nt
	s_add_i32 s14, s14, 16
	s_add_i32 s15, s15, 16
	s_add_i32 s13, s13, -16
	v_mad_u64_u32 v[20:21], s[26:27], v11, s10, v[2:3]
	s_cmp_lg_u32 s13, 0
	v_mad_u64_u32 v[22:23], s[26:27], v9, s10, v[2:3]
	v_mad_u64_u32 v[24:25], s[26:27], v53, s10, v[2:3]
	v_mad_u64_u32 v[26:27], s[26:27], v52, s10, v[2:3]
	v_mad_u64_u32 v[28:29], s[26:27], v55, s10, v[2:3]
	v_mad_u64_u32 v[30:31], s[26:27], v54, s10, v[2:3]
	v_mad_u64_u32 v[32:33], s[26:27], v57, s10, v[2:3]
	v_mad_u64_u32 v[34:35], s[26:27], v56, s10, v[2:3]
	v_mad_u64_u32 v[36:37], s[26:27], v59, s10, v[2:3]
	v_mad_u64_u32 v[38:39], s[26:27], v58, s10, v[2:3]
	v_mad_u64_u32 v[40:41], s[26:27], v61, s10, v[2:3]
	v_mad_u64_u32 v[42:43], s[26:27], v60, s10, v[2:3]
	v_mad_u64_u32 v[44:45], s[26:27], v63, s10, v[2:3]
	v_mad_u64_u32 v[46:47], s[26:27], v62, s10, v[2:3]
	v_mad_u64_u32 v[48:49], s[26:27], v65, s10, v[2:3]
	v_mad_u64_u32 v[50:51], s[26:27], v64, s10, v[2:3]
	s_waitcnt vmcnt(15)
	ds_write_b32 v20, v66
	s_waitcnt vmcnt(14)
	ds_write_b32 v22, v67
	s_waitcnt vmcnt(13)
	ds_write_b32 v24, v68
	s_waitcnt vmcnt(12)
	ds_write_b32 v26, v69
	s_waitcnt vmcnt(11)
	ds_write_b32 v28, v70
	s_waitcnt vmcnt(10)
	ds_write_b32 v30, v71
	s_waitcnt vmcnt(9)
	ds_write_b32 v32, v72
	s_waitcnt vmcnt(8)
	ds_write_b32 v34, v73
	s_waitcnt vmcnt(7)
	ds_write_b32 v36, v74
	s_waitcnt vmcnt(6)
	ds_write_b32 v38, v75
	s_waitcnt vmcnt(5)
	ds_write_b32 v40, v76
	s_waitcnt vmcnt(4)
	ds_write_b32 v42, v77
	s_waitcnt vmcnt(3)
	ds_write_b32 v44, v78
	s_waitcnt vmcnt(2)
	ds_write_b32 v46, v79
	s_waitcnt vmcnt(1)
	ds_write_b32 v48, v80
	s_waitcnt vmcnt(0)
	ds_write_b32 v50, v81
	s_cbranch_scc1 .LBB0_406
	s_waitcnt lgkmcnt(0)
	ds_read2_b32 v[20:21], v16 offset0:33 offset1:41
	ds_read2_b32 v[22:23], v16 offset1:8
	ds_read2_b32 v[24:25], v16 offset0:66 offset1:74
	ds_read2_b32 v[26:27], v16 offset0:99 offset1:107
	ds_read2_b32 v[28:29], v16 offset0:132 offset1:140
	ds_read2_b32 v[30:31], v16 offset0:165 offset1:173
	ds_read2_b32 v[32:33], v16 offset0:198 offset1:206
	ds_read2_b32 v[34:35], v16 offset0:231 offset1:239
	v_ashrrev_i32_e32 v11, 31, v10
	v_lshl_add_u64 v[36:37], v[10:11], 1, v[6:7]
	v_or_b32_e32 v3, v8, v15
	s_waitcnt lgkmcnt(6)
	v_cvt_pk_bf16_f32 v10, v22, v20
	s_waitcnt lgkmcnt(4)
	v_cvt_pk_bf16_f32 v11, v24, v26
	s_waitcnt lgkmcnt(2)
	v_cvt_pk_bf16_f32 v12, v28, v30
	s_waitcnt lgkmcnt(0)
	v_cvt_pk_bf16_f32 v13, v32, v34
	v_mad_i64_i32 v[38:39], s[14:15], v3, s11, v[36:37]
	global_store_dwordx4 v[38:39], v[10:13], off
	v_or_b32_e32 v3, v8, v17
	v_add_u32_e32 v14, s9, v14
	v_cvt_pk_bf16_f32 v10, v23, v21
	v_cvt_pk_bf16_f32 v11, v25, v27
	v_cvt_pk_bf16_f32 v12, v29, v31
	v_cvt_pk_bf16_f32 v13, v33, v35
	ds_read2_b32 v[22:23], v16 offset0:49 offset1:57
	ds_read2_b32 v[24:25], v16 offset0:16 offset1:24
	ds_read2_b32 v[26:27], v16 offset0:82 offset1:90
	ds_read2_b32 v[28:29], v16 offset0:115 offset1:123
	ds_read2_b32 v[30:31], v16 offset0:148 offset1:156
	ds_read2_b32 v[32:33], v16 offset0:181 offset1:189
	ds_read2_b32 v[34:35], v16 offset0:214 offset1:222
	ds_read2_b32 v[38:39], v16 offset0:247 offset1:255
	v_mad_i64_i32 v[20:21], s[14:15], v3, s11, v[36:37]
	v_or_b32_e32 v3, v8, v18
	global_store_dwordx4 v[20:21], v[10:13], off
	v_mad_i64_i32 v[20:21], s[14:15], v3, s11, v[36:37]
	s_waitcnt lgkmcnt(6)
	v_cvt_pk_bf16_f32 v10, v24, v22
	s_waitcnt lgkmcnt(4)
	v_cvt_pk_bf16_f32 v11, v26, v28
	s_waitcnt lgkmcnt(2)
	v_cvt_pk_bf16_f32 v12, v30, v32
	s_waitcnt lgkmcnt(0)
	v_cvt_pk_bf16_f32 v13, v34, v38
	v_or_b32_e32 v3, v8, v19
	global_store_dwordx4 v[20:21], v[10:13], off
	v_mad_i64_i32 v[8:9], s[14:15], v3, s11, v[36:37]
	s_nop 0
	v_cvt_pk_bf16_f32 v10, v25, v23
	v_cvt_pk_bf16_f32 v11, v27, v29
	v_cvt_pk_bf16_f32 v12, v31, v33
	v_cvt_pk_bf16_f32 v13, v35, v39
	global_store_dwordx4 v[8:9], v[10:13], off
	s_waitcnt lgkmcnt(0)
	v_cmp_lt_i32_e32 vcc, s12, v14
	s_or_b64 s[6:7], vcc, s[6:7]
	s_andn2_b64 exec, exec, s[6:7]
	s_cbranch_execnz .LBB0_405

.LBB0_415:
	s_lshl_b32 s26, s15, 1
	s_lshl_b32 s27, s14, 1
	v_or_b32_e32 v11, s26, v1
	v_or_b32_e32 v13, s27, v2
	s_add_i32 s28, s26, 4
	s_add_i32 s29, s27, 4
	s_add_i32 s30, s26, 8
	s_add_i32 s31, s27, 8
	s_add_i32 s33, s26, 12
	s_add_i32 s35, s27, 12
	s_add_i32 s52, s26, 16
	s_add_i32 s53, s27, 16
	s_add_i32 s54, s26, 20
	s_add_i32 s55, s27, 20
	s_add_i32 s56, s26, 24
	s_add_i32 s57, s27, 24
	s_add_i32 s26, s26, 28
	s_add_i32 s27, s27, 28
	v_add_u32_e32 v15, v11, v3
	v_add_u32_e32 v22, v13, v10
	v_or_b32_e32 v54, s28, v1
	v_or_b32_e32 v55, s29, v2
	v_or_b32_e32 v56, s30, v1
	v_or_b32_e32 v57, s31, v2
	v_or_b32_e32 v58, s33, v1
	v_or_b32_e32 v59, s35, v2
	v_or_b32_e32 v60, s52, v1
	v_or_b32_e32 v61, s53, v2
	v_or_b32_e32 v62, s54, v1
	v_or_b32_e32 v63, s55, v2
	v_or_b32_e32 v64, s56, v1
	v_or_b32_e32 v65, s57, v2
	v_or_b32_e32 v66, s26, v1
	v_or_b32_e32 v67, s27, v2
	v_mad_i64_i32 v[22:23], s[26:27], v22, s10, v[16:17]
	v_mad_i64_i32 v[24:25], s[26:27], v15, s10, v[16:17]
	v_add_u32_e32 v15, v54, v3
	v_add_u32_e32 v26, v55, v10
	v_add_u32_e32 v32, v56, v3
	v_add_u32_e32 v30, v57, v10
	v_add_u32_e32 v36, v58, v3
	v_add_u32_e32 v34, v59, v10
	v_add_u32_e32 v40, v60, v3
	v_add_u32_e32 v38, v61, v10
	v_add_u32_e32 v44, v62, v3
	v_add_u32_e32 v42, v63, v10
	v_add_u32_e32 v48, v64, v3
	v_add_u32_e32 v46, v65, v10
	v_add_u32_e32 v52, v66, v3
	v_add_u32_e32 v50, v67, v10
	v_mad_i64_i32 v[26:27], s[26:27], v26, s10, v[16:17]
	v_mad_i64_i32 v[28:29], s[26:27], v15, s10, v[16:17]
	v_mad_i64_i32 v[30:31], s[26:27], v30, s10, v[16:17]
	v_mad_i64_i32 v[32:33], s[26:27], v32, s10, v[16:17]
	v_mad_i64_i32 v[34:35], s[26:27], v34, s10, v[16:17]
	v_mad_i64_i32 v[36:37], s[26:27], v36, s10, v[16:17]
	v_mad_i64_i32 v[38:39], s[26:27], v38, s10, v[16:17]
	v_mad_i64_i32 v[40:41], s[26:27], v40, s10, v[16:17]
	v_mad_i64_i32 v[42:43], s[26:27], v42, s10, v[16:17]
	v_mad_i64_i32 v[44:45], s[26:27], v44, s10, v[16:17]
	v_mad_i64_i32 v[46:47], s[26:27], v46, s10, v[16:17]
	v_mad_i64_i32 v[48:49], s[26:27], v48, s10, v[16:17]
	v_mad_i64_i32 v[50:51], s[26:27], v50, s10, v[16:17]
	v_mad_i64_i32 v[52:53], s[26:27], v52, s10, v[16:17]
	global_load_dword v15, v[22:23], off nt
	global_load_dword v68, v[24:25], off nt
	global_load_dword v69, v[26:27], off nt
	global_load_dword v70, v[28:29], off nt
	global_load_dword v71, v[30:31], off nt
	global_load_dword v72, v[32:33], off nt
	global_load_dword v73, v[34:35], off nt
	global_load_dword v74, v[36:37], off nt
	global_load_dword v75, v[38:39], off nt
	global_load_dword v76, v[40:41], off nt
	global_load_dword v77, v[42:43], off nt
	global_load_dword v78, v[44:45], off nt
	global_load_dword v79, v[46:47], off nt
	global_load_dword v80, v[48:49], off nt
	global_load_dword v81, v[50:51], off nt
	global_load_dword v82, v[52:53], off nt
	s_add_i32 s14, s14, 16
	s_add_i32 s15, s15, 16
	s_add_i32 s13, s13, -16
	v_mad_u64_u32 v[22:23], s[26:27], v13, s7, v[4:5]
	s_cmp_lg_u32 s13, 0
	v_mad_u64_u32 v[24:25], s[26:27], v11, s7, v[4:5]
	v_mad_u64_u32 v[26:27], s[26:27], v55, s7, v[4:5]
	v_mad_u64_u32 v[28:29], s[26:27], v54, s7, v[4:5]
	v_mad_u64_u32 v[30:31], s[26:27], v57, s7, v[4:5]
	v_mad_u64_u32 v[32:33], s[26:27], v56, s7, v[4:5]
	v_mad_u64_u32 v[34:35], s[26:27], v59, s7, v[4:5]
	v_mad_u64_u32 v[36:37], s[26:27], v58, s7, v[4:5]
	v_mad_u64_u32 v[38:39], s[26:27], v61, s7, v[4:5]
	v_mad_u64_u32 v[40:41], s[26:27], v60, s7, v[4:5]
	v_mad_u64_u32 v[42:43], s[26:27], v63, s7, v[4:5]
	v_mad_u64_u32 v[44:45], s[26:27], v62, s7, v[4:5]
	v_mad_u64_u32 v[46:47], s[26:27], v65, s7, v[4:5]
	v_mad_u64_u32 v[48:49], s[26:27], v64, s7, v[4:5]
	v_mad_u64_u32 v[50:51], s[26:27], v67, s7, v[4:5]
	v_mad_u64_u32 v[52:53], s[26:27], v66, s7, v[4:5]
	s_waitcnt vmcnt(15)
	ds_write_b32 v22, v15
	s_waitcnt vmcnt(14)
	ds_write_b32 v24, v68
	s_waitcnt vmcnt(13)
	ds_write_b32 v26, v69
	s_waitcnt vmcnt(12)
	ds_write_b32 v28, v70
	s_waitcnt vmcnt(11)
	ds_write_b32 v30, v71
	s_waitcnt vmcnt(10)
	ds_write_b32 v32, v72
	s_waitcnt vmcnt(9)
	ds_write_b32 v34, v73
	s_waitcnt vmcnt(8)
	ds_write_b32 v36, v74
	s_waitcnt vmcnt(7)
	ds_write_b32 v38, v75
	s_waitcnt vmcnt(6)
	ds_write_b32 v40, v76
	s_waitcnt vmcnt(5)
	ds_write_b32 v42, v77
	s_waitcnt vmcnt(4)
	ds_write_b32 v44, v78
	s_waitcnt vmcnt(3)
	ds_write_b32 v46, v79
	s_waitcnt vmcnt(2)
	ds_write_b32 v48, v80
	s_waitcnt vmcnt(1)
	ds_write_b32 v50, v81
	s_waitcnt vmcnt(0)
	ds_write_b32 v52, v82
	s_cbranch_scc1 .LBB0_415
	v_lshlrev_b32_e32 v3, 6, v12
	v_and_b32_e32 v3, 0xffffff00, v3
	s_waitcnt lgkmcnt(0)
	v_and_or_b32 v3, v14, s11, v3
	ds_read2_b32 v[14:15], v18 offset0:33 offset1:41
	ds_read2_b32 v[16:17], v18 offset1:8
	ds_read2_b32 v[22:23], v18 offset0:66 offset1:74
	ds_read2_b32 v[24:25], v18 offset0:99 offset1:107
	ds_read2_b32 v[26:27], v18 offset0:132 offset1:140
	ds_read2_b32 v[28:29], v18 offset0:165 offset1:173
	ds_read2_b32 v[30:31], v18 offset0:198 offset1:206
	ds_read2_b32 v[32:33], v18 offset0:231 offset1:239
	v_or_b32_e32 v36, v3, v5
	v_ashrrev_i32_e32 v11, 31, v10
	v_ashrrev_i32_e32 v37, 31, v36
	v_lshl_add_u64 v[34:35], v[10:11], 1, v[8:9]
	v_lshlrev_b64 v[36:37], 12, v[36:37]
	s_waitcnt lgkmcnt(6)
	v_cvt_pk_bf16_f32 v10, v16, v14
	s_waitcnt lgkmcnt(4)
	v_cvt_pk_bf16_f32 v11, v22, v24
	s_waitcnt lgkmcnt(2)
	v_cvt_pk_bf16_f32 v12, v26, v28
	s_waitcnt lgkmcnt(0)
	v_cvt_pk_bf16_f32 v13, v30, v32
	v_lshl_add_u64 v[36:37], v[34:35], 0, v[36:37]
	v_or_b32_e32 v14, v3, v19
	global_store_dwordx4 v[36:37], v[10:13], off
	v_add_u32_e32 v0, s6, v0
	v_cmp_lt_i32_e32 vcc, s12, v0
	v_cvt_pk_bf16_f32 v10, v17, v15
	v_ashrrev_i32_e32 v15, 31, v14
	v_cvt_pk_bf16_f32 v11, v23, v25
	v_cvt_pk_bf16_f32 v12, v27, v29
	v_cvt_pk_bf16_f32 v13, v31, v33
	v_lshlrev_b64 v[14:15], 12, v[14:15]
	ds_read2_b32 v[16:17], v18 offset0:49 offset1:57
	ds_read2_b32 v[22:23], v18 offset0:16 offset1:24
	ds_read2_b32 v[24:25], v18 offset0:82 offset1:90
	ds_read2_b32 v[26:27], v18 offset0:115 offset1:123
	ds_read2_b32 v[28:29], v18 offset0:148 offset1:156
	ds_read2_b32 v[30:31], v18 offset0:181 offset1:189
	ds_read2_b32 v[32:33], v18 offset0:214 offset1:222
	ds_read2_b32 v[36:37], v18 offset0:247 offset1:255
	v_lshl_add_u64 v[14:15], v[34:35], 0, v[14:15]
	global_store_dwordx4 v[14:15], v[10:13], off
	v_or_b32_e32 v14, v3, v20
	v_ashrrev_i32_e32 v15, 31, v14
	v_lshlrev_b64 v[14:15], 12, v[14:15]
	s_waitcnt lgkmcnt(6)
	v_cvt_pk_bf16_f32 v10, v22, v16
	s_waitcnt lgkmcnt(4)
	v_cvt_pk_bf16_f32 v11, v24, v26
	s_waitcnt lgkmcnt(2)
	v_cvt_pk_bf16_f32 v12, v28, v30
	s_waitcnt lgkmcnt(0)
	v_cvt_pk_bf16_f32 v13, v32, v36
	v_lshl_add_u64 v[14:15], v[34:35], 0, v[14:15]
	global_store_dwordx4 v[14:15], v[10:13], off
	v_or_b32_e32 v14, v3, v21
	v_ashrrev_i32_e32 v15, 31, v14
	v_lshlrev_b64 v[14:15], 12, v[14:15]
	v_cvt_pk_bf16_f32 v10, v23, v17
	v_cvt_pk_bf16_f32 v11, v25, v27
	v_cvt_pk_bf16_f32 v12, v29, v31
	v_cvt_pk_bf16_f32 v13, v33, v37
	v_lshl_add_u64 v[14:15], v[34:35], 0, v[14:15]
	global_store_dwordx4 v[14:15], v[10:13], off
	s_waitcnt lgkmcnt(0)
	s_or_b64 s[4:5], vcc, s[4:5]
	s_andn2_b64 exec, exec, s[4:5]
	s_cbranch_execnz .LBB0_414

.LBB0_581:
	s_lshl_b32 s57, s54, 1
	s_lshl_b32 s58, s55, 1
	v_or_b32_e32 v11, s57, v1
	v_or_b32_e32 v17, s58, v4
	s_add_i32 s59, s57, 4
	s_add_i32 s60, s58, 4
	s_add_i32 s61, s57, 8
	s_add_i32 s62, s58, 8
	s_add_i32 s63, s57, 12
	s_add_i32 s64, s58, 12
	s_add_i32 s65, s57, 16
	s_add_i32 s66, s58, 16
	s_add_i32 s67, s57, 20
	s_add_i32 s73, s58, 20
	s_add_i32 s74, s57, 24
	s_add_i32 s75, s58, 24
	s_add_i32 s57, s57, 28
	s_add_i32 s58, s58, 28
	v_add_u32_e32 v25, v11, v3
	v_add_u32_e32 v28, v17, v16
	v_or_b32_e32 v87, s59, v1
	v_or_b32_e32 v89, s60, v4
	v_or_b32_e32 v90, s61, v1
	v_or_b32_e32 v91, s62, v4
	v_or_b32_e32 v92, s63, v1
	v_or_b32_e32 v93, s64, v4
	v_or_b32_e32 v94, s65, v1
	v_or_b32_e32 v95, s66, v4
	v_or_b32_e32 v96, s67, v1
	v_or_b32_e32 v97, s73, v4
	v_or_b32_e32 v98, s74, v1
	v_or_b32_e32 v99, s75, v4
	v_or_b32_e32 v100, s57, v1
	v_or_b32_e32 v101, s58, v4
	v_ashrrev_i32_e32 v33, 31, v28
	v_ashrrev_i32_e32 v31, 31, v25
	v_mad_u64_u32 v[26:27], s[58:59], v2, v25, 0
	v_mad_u64_u32 v[28:29], s[58:59], v0, v28, 0
	v_add_u32_e32 v25, v87, v3
	v_add_u32_e32 v36, v89, v16
	v_add_u32_e32 v38, v90, v3
	v_add_u32_e32 v40, v91, v16
	v_add_u32_e32 v42, v92, v3
	v_add_u32_e32 v44, v93, v16
	v_add_u32_e32 v46, v94, v3
	v_add_u32_e32 v48, v95, v16
	v_add_u32_e32 v50, v96, v3
	v_add_u32_e32 v52, v97, v16
	v_add_u32_e32 v54, v98, v3
	v_add_u32_e32 v56, v99, v16
	v_add_u32_e32 v58, v100, v3
	v_add_u32_e32 v60, v101, v16
	v_mov_b32_e32 v30, v27
	v_mov_b32_e32 v32, v29
	v_ashrrev_i32_e32 v63, 31, v36
	v_ashrrev_i32_e32 v65, 31, v25
	v_mad_u64_u32 v[34:35], s[58:59], v2, v25, 0
	v_mad_u64_u32 v[36:37], s[58:59], v0, v36, 0
	v_ashrrev_i32_e32 v25, 31, v40
	v_ashrrev_i32_e32 v67, 31, v38
	v_mad_u64_u32 v[38:39], s[58:59], v2, v38, 0
	v_mad_u64_u32 v[40:41], s[58:59], v0, v40, 0
	v_ashrrev_i32_e32 v69, 31, v44
	v_ashrrev_i32_e32 v71, 31, v42
	v_mad_u64_u32 v[42:43], s[58:59], v2, v42, 0
	v_mad_u64_u32 v[44:45], s[58:59], v0, v44, 0
	v_ashrrev_i32_e32 v73, 31, v48
	v_ashrrev_i32_e32 v75, 31, v46
	v_mad_u64_u32 v[46:47], s[58:59], v2, v46, 0
	v_mad_u64_u32 v[48:49], s[58:59], v0, v48, 0
	v_ashrrev_i32_e32 v77, 31, v52
	v_ashrrev_i32_e32 v79, 31, v50
	v_mad_u64_u32 v[50:51], s[58:59], v2, v50, 0
	v_mad_u64_u32 v[52:53], s[58:59], v0, v52, 0
	v_ashrrev_i32_e32 v81, 31, v56
	v_ashrrev_i32_e32 v83, 31, v54
	v_mad_u64_u32 v[54:55], s[58:59], v2, v54, 0
	v_mad_u64_u32 v[56:57], s[58:59], v0, v56, 0
	v_ashrrev_i32_e32 v85, 31, v60
	v_ashrrev_i32_e32 v102, 31, v58
	v_mad_u64_u32 v[58:59], s[58:59], v2, v58, 0
	v_mad_u64_u32 v[60:61], s[58:59], v0, v60, 0
	v_mad_u64_u32 v[30:31], s[58:59], v2, v31, v[30:31]
	v_mad_u64_u32 v[32:33], s[58:59], v0, v33, v[32:33]
	v_mov_b32_e32 v62, v35
	v_mov_b32_e32 v64, v37
	v_mov_b32_e32 v66, v39
	v_mov_b32_e32 v68, v41
	v_mov_b32_e32 v70, v43
	v_mov_b32_e32 v72, v45
	v_mov_b32_e32 v74, v47
	v_mov_b32_e32 v76, v49
	v_mov_b32_e32 v78, v51
	v_mov_b32_e32 v80, v53
	v_mov_b32_e32 v82, v55
	v_mov_b32_e32 v84, v57
	v_mov_b32_e32 v86, v59
	v_mov_b32_e32 v88, v61
	v_mov_b32_e32 v27, v30
	v_mov_b32_e32 v29, v32
	v_mad_u64_u32 v[30:31], s[58:59], v2, v65, v[62:63]
	v_mad_u64_u32 v[32:33], s[58:59], v0, v63, v[64:65]
	v_mad_u64_u32 v[62:63], s[58:59], v2, v67, v[66:67]
	v_mad_u64_u32 v[64:65], s[58:59], v0, v25, v[68:69]
	v_mad_u64_u32 v[66:67], s[58:59], v2, v71, v[70:71]
	v_mad_u64_u32 v[68:69], s[58:59], v0, v69, v[72:73]
	v_mad_u64_u32 v[70:71], s[58:59], v2, v75, v[74:75]
	v_mad_u64_u32 v[72:73], s[58:59], v0, v73, v[76:77]
	v_mad_u64_u32 v[74:75], s[58:59], v2, v79, v[78:79]
	v_mad_u64_u32 v[76:77], s[58:59], v0, v77, v[80:81]
	v_mad_u64_u32 v[78:79], s[58:59], v2, v83, v[82:83]
	v_mad_u64_u32 v[80:81], s[58:59], v0, v81, v[84:85]
	v_mad_u64_u32 v[82:83], s[58:59], v2, v102, v[86:87]
	v_mad_u64_u32 v[84:85], s[58:59], v0, v85, v[88:89]
	v_lshl_add_u64 v[28:29], v[28:29], 2, v[18:19]
	v_mov_b32_e32 v35, v30
	v_mov_b32_e32 v37, v32
	v_mov_b32_e32 v39, v62
	v_mov_b32_e32 v41, v64
	v_mov_b32_e32 v43, v66
	v_mov_b32_e32 v45, v68
	v_mov_b32_e32 v47, v70
	v_mov_b32_e32 v49, v72
	v_mov_b32_e32 v51, v74
	v_mov_b32_e32 v53, v76
	v_mov_b32_e32 v55, v78
	v_mov_b32_e32 v57, v80
	v_mov_b32_e32 v59, v82
	v_mov_b32_e32 v61, v84
	v_lshl_add_u64 v[26:27], v[26:27], 2, v[18:19]
	v_lshl_add_u64 v[30:31], v[36:37], 2, v[18:19]
	v_lshl_add_u64 v[32:33], v[34:35], 2, v[18:19]
	v_lshl_add_u64 v[34:35], v[40:41], 2, v[18:19]
	v_lshl_add_u64 v[36:37], v[38:39], 2, v[18:19]
	v_lshl_add_u64 v[38:39], v[44:45], 2, v[18:19]
	v_lshl_add_u64 v[40:41], v[42:43], 2, v[18:19]
	v_lshl_add_u64 v[42:43], v[48:49], 2, v[18:19]
	v_lshl_add_u64 v[44:45], v[46:47], 2, v[18:19]
	v_lshl_add_u64 v[46:47], v[52:53], 2, v[18:19]
	v_lshl_add_u64 v[48:49], v[50:51], 2, v[18:19]
	v_lshl_add_u64 v[50:51], v[56:57], 2, v[18:19]
	v_lshl_add_u64 v[52:53], v[54:55], 2, v[18:19]
	v_lshl_add_u64 v[54:55], v[60:61], 2, v[18:19]
	v_lshl_add_u64 v[56:57], v[58:59], 2, v[18:19]
	global_load_dword v25, v[28:29], off nt
	global_load_dword v58, v[26:27], off nt
	global_load_dword v59, v[30:31], off nt
	global_load_dword v60, v[32:33], off nt
	global_load_dword v61, v[34:35], off nt
	global_load_dword v62, v[36:37], off nt
	global_load_dword v63, v[38:39], off nt
	global_load_dword v64, v[40:41], off nt
	global_load_dword v65, v[42:43], off nt
	global_load_dword v66, v[44:45], off nt
	global_load_dword v67, v[46:47], off nt
	global_load_dword v68, v[48:49], off nt
	global_load_dword v69, v[50:51], off nt
	global_load_dword v70, v[52:53], off nt
	global_load_dword v71, v[54:55], off nt
	global_load_dword v72, v[56:57], off nt
	s_add_i32 s55, s55, 16
	s_add_i32 s54, s54, 16
	s_add_i32 s56, s56, -16
	v_mad_u64_u32 v[26:27], s[58:59], v17, s68, v[8:9]
	s_cmp_lg_u32 s56, 0
	v_mad_u64_u32 v[28:29], s[58:59], v11, s68, v[8:9]
	v_mad_u64_u32 v[30:31], s[58:59], v89, s68, v[8:9]
	v_mad_u64_u32 v[32:33], s[58:59], v87, s68, v[8:9]
	v_mad_u64_u32 v[34:35], s[58:59], v91, s68, v[8:9]
	v_mad_u64_u32 v[36:37], s[58:59], v90, s68, v[8:9]
	v_mad_u64_u32 v[38:39], s[58:59], v93, s68, v[8:9]
	v_mad_u64_u32 v[40:41], s[58:59], v92, s68, v[8:9]
	v_mad_u64_u32 v[42:43], s[58:59], v95, s68, v[8:9]
	v_mad_u64_u32 v[44:45], s[58:59], v94, s68, v[8:9]
	v_mad_u64_u32 v[46:47], s[58:59], v97, s68, v[8:9]
	v_mad_u64_u32 v[48:49], s[58:59], v96, s68, v[8:9]
	v_mad_u64_u32 v[50:51], s[58:59], v99, s68, v[8:9]
	v_mad_u64_u32 v[52:53], s[58:59], v98, s68, v[8:9]
	v_mad_u64_u32 v[54:55], s[58:59], v101, s68, v[8:9]
	v_mad_u64_u32 v[56:57], s[58:59], v100, s68, v[8:9]
	s_waitcnt vmcnt(15)
	ds_write_b32 v26, v25
	s_waitcnt vmcnt(14)
	ds_write_b32 v28, v58
	s_waitcnt vmcnt(13)
	ds_write_b32 v30, v59
	s_waitcnt vmcnt(12)
	ds_write_b32 v32, v60
	s_waitcnt vmcnt(11)
	ds_write_b32 v34, v61
	s_waitcnt vmcnt(10)
	ds_write_b32 v36, v62
	s_waitcnt vmcnt(9)
	ds_write_b32 v38, v63
	s_waitcnt vmcnt(8)
	ds_write_b32 v40, v64
	s_waitcnt vmcnt(7)
	ds_write_b32 v42, v65
	s_waitcnt vmcnt(6)
	ds_write_b32 v44, v66
	s_waitcnt vmcnt(5)
	ds_write_b32 v46, v67
	s_waitcnt vmcnt(4)
	ds_write_b32 v48, v68
	s_waitcnt vmcnt(3)
	ds_write_b32 v50, v69
	s_waitcnt vmcnt(2)
	ds_write_b32 v52, v70
	s_waitcnt vmcnt(1)
	ds_write_b32 v54, v71
	s_waitcnt vmcnt(0)
	ds_write_b32 v56, v72
	s_cbranch_scc1 .LBB0_581
	s_waitcnt lgkmcnt(0)
	v_ashrrev_i32_e32 v17, 31, v16
	ds_read2_b32 v[18:19], v20 offset0:33 offset1:41
	ds_read2_b32 v[26:27], v20 offset1:8
	ds_read2_b32 v[28:29], v20 offset0:66 offset1:74
	ds_read2_b32 v[30:31], v20 offset0:99 offset1:107
	ds_read2_b32 v[32:33], v20 offset0:132 offset1:140
	ds_read2_b32 v[34:35], v20 offset0:165 offset1:173
	ds_read2_b32 v[36:37], v20 offset0:198 offset1:206
	ds_read2_b32 v[38:39], v20 offset0:231 offset1:239
	v_lshl_add_u64 v[2:3], v[16:17], 1, v[14:15]
	v_mov_b32_e32 v11, v7
	v_add_u32_e32 v0, v24, v9
	v_lshl_add_u64 v[2:3], v[2:3], 0, v[10:11]
	v_ashrrev_i32_e32 v11, 31, v0
	s_waitcnt lgkmcnt(6)
	v_cvt_pk_bf16_f32 v14, v26, v18
	v_mul_lo_u32 v11, v12, v11
	v_mul_lo_u32 v18, v13, v0
	v_mad_u64_u32 v[40:41], s[54:55], v12, v0, 0
	v_add3_u32 v41, v41, v11, v18
	s_waitcnt lgkmcnt(4)
	v_cvt_pk_bf16_f32 v15, v28, v30
	s_waitcnt lgkmcnt(2)
	v_cvt_pk_bf16_f32 v16, v32, v34
	s_waitcnt lgkmcnt(0)
	v_cvt_pk_bf16_f32 v17, v36, v38
	v_lshl_add_u64 v[40:41], v[40:41], 1, v[2:3]
	v_add_u32_e32 v0, v24, v21
	global_store_dwordx4 v[40:41], v[14:17], off
	v_ashrrev_i32_e32 v11, 31, v0
	v_mul_lo_u32 v11, v12, v11
	v_cvt_pk_bf16_f32 v14, v27, v19
	v_cvt_pk_bf16_f32 v15, v29, v31
	v_cvt_pk_bf16_f32 v16, v33, v35
	v_cvt_pk_bf16_f32 v17, v37, v39
	v_mul_lo_u32 v25, v13, v0
	v_mad_u64_u32 v[18:19], s[54:55], v12, v0, 0
	ds_read2_b32 v[26:27], v20 offset0:16 offset1:24
	ds_read2_b32 v[28:29], v20 offset0:49 offset1:57
	ds_read2_b32 v[30:31], v20 offset0:82 offset1:90
	ds_read2_b32 v[32:33], v20 offset0:115 offset1:123
	ds_read2_b32 v[34:35], v20 offset0:148 offset1:156
	ds_read2_b32 v[36:37], v20 offset0:181 offset1:189
	ds_read2_b32 v[38:39], v20 offset0:214 offset1:222
	ds_read2_b32 v[40:41], v20 offset0:247 offset1:255
	v_add3_u32 v19, v19, v11, v25
	v_add_u32_e32 v0, v24, v22
	v_lshl_add_u64 v[18:19], v[18:19], 1, v[2:3]
	v_ashrrev_i32_e32 v11, 31, v0
	global_store_dwordx4 v[18:19], v[14:17], off
	v_mul_lo_u32 v11, v12, v11
	v_mul_lo_u32 v25, v13, v0
	v_mad_u64_u32 v[18:19], s[54:55], v12, v0, 0
	v_add3_u32 v19, v19, v11, v25
	v_add_u32_e32 v0, v24, v23
	s_waitcnt lgkmcnt(6)
	v_cvt_pk_bf16_f32 v14, v26, v28
	s_waitcnt lgkmcnt(4)
	v_cvt_pk_bf16_f32 v15, v30, v32
	s_waitcnt lgkmcnt(2)
	v_cvt_pk_bf16_f32 v16, v34, v36
	s_waitcnt lgkmcnt(0)
	v_cvt_pk_bf16_f32 v17, v38, v40
	v_lshl_add_u64 v[18:19], v[18:19], 1, v[2:3]
	v_ashrrev_i32_e32 v11, 31, v0
	global_store_dwordx4 v[18:19], v[14:17], off
	v_mul_lo_u32 v11, v12, v11
	v_mul_lo_u32 v18, v13, v0
	v_mad_u64_u32 v[12:13], s[54:55], v12, v0, 0
	v_add3_u32 v13, v13, v11, v18
	v_cvt_pk_bf16_f32 v14, v27, v29
	v_cvt_pk_bf16_f32 v15, v31, v33
	v_cvt_pk_bf16_f32 v16, v35, v37
	v_cvt_pk_bf16_f32 v17, v39, v41
	v_lshl_add_u64 v[2:3], v[12:13], 1, v[2:3]
	global_store_dwordx4 v[2:3], v[14:17], off
	v_add_u32_e32 v5, s35, v5
	s_waitcnt lgkmcnt(0)
	v_cmp_lt_i32_e32 vcc, s72, v5
	s_or_b64 s[52:53], vcc, s[52:53]
	s_andn2_b64 exec, exec, s[52:53]
	s_cbranch_execnz .LBB0_512

.LBB0_592:
	s_lshl_b32 s27, s6, 1
	s_lshl_b32 s28, s7, 1
	v_or_b32_e32 v9, s27, v1
	v_or_b32_e32 v19, s28, v0
	s_add_i32 s29, s27, 4
	s_add_i32 s30, s28, 4
	s_add_i32 s31, s27, 8
	s_add_i32 s33, s28, 8
	s_add_i32 s35, s27, 12
	s_add_i32 s52, s28, 12
	s_add_i32 s53, s27, 16
	s_add_i32 s54, s28, 16
	s_add_i32 s55, s27, 20
	s_add_i32 s56, s28, 20
	s_add_i32 s57, s27, 24
	s_add_i32 s58, s28, 24
	s_add_i32 s27, s27, 28
	s_add_i32 s28, s28, 28
	v_add_u32_e32 v20, v19, v8
	v_or_b32_e32 v52, s29, v1
	v_or_b32_e32 v53, s30, v0
	v_or_b32_e32 v54, s31, v1
	v_or_b32_e32 v55, s33, v0
	v_or_b32_e32 v56, s35, v1
	v_or_b32_e32 v57, s52, v0
	v_or_b32_e32 v58, s53, v1
	v_or_b32_e32 v59, s54, v0
	v_or_b32_e32 v60, s55, v1
	v_or_b32_e32 v61, s56, v0
	v_or_b32_e32 v62, s57, v1
	v_or_b32_e32 v63, s58, v0
	v_or_b32_e32 v64, s27, v1
	v_or_b32_e32 v65, s28, v0
	v_add_u32_e32 v22, v9, v3
	v_mad_i64_i32 v[20:21], s[28:29], v20, s14, v[10:11]
	v_add_u32_e32 v26, v52, v3
	v_add_u32_e32 v24, v53, v8
	v_add_u32_e32 v30, v54, v3
	v_add_u32_e32 v28, v55, v8
	v_add_u32_e32 v34, v56, v3
	v_add_u32_e32 v32, v57, v8
	v_add_u32_e32 v38, v58, v3
	v_add_u32_e32 v36, v59, v8
	v_add_u32_e32 v42, v60, v3
	v_add_u32_e32 v40, v61, v8
	v_add_u32_e32 v46, v62, v3
	v_add_u32_e32 v44, v63, v8
	v_add_u32_e32 v50, v64, v3
	v_add_u32_e32 v48, v65, v8
	v_mad_i64_i32 v[22:23], s[28:29], v22, s14, v[10:11]
	v_mad_i64_i32 v[24:25], s[28:29], v24, s14, v[10:11]
	v_mad_i64_i32 v[26:27], s[28:29], v26, s14, v[10:11]
	v_mad_i64_i32 v[28:29], s[28:29], v28, s14, v[10:11]
	v_mad_i64_i32 v[30:31], s[28:29], v30, s14, v[10:11]
	v_mad_i64_i32 v[32:33], s[28:29], v32, s14, v[10:11]
	v_mad_i64_i32 v[34:35], s[28:29], v34, s14, v[10:11]
	v_mad_i64_i32 v[36:37], s[28:29], v36, s14, v[10:11]
	v_mad_i64_i32 v[38:39], s[28:29], v38, s14, v[10:11]
	v_mad_i64_i32 v[40:41], s[28:29], v40, s14, v[10:11]
	v_mad_i64_i32 v[42:43], s[28:29], v42, s14, v[10:11]
	v_mad_i64_i32 v[44:45], s[28:29], v44, s14, v[10:11]
	v_mad_i64_i32 v[46:47], s[28:29], v46, s14, v[10:11]
	v_mad_i64_i32 v[48:49], s[28:29], v48, s14, v[10:11]
	v_mad_i64_i32 v[50:51], s[28:29], v50, s14, v[10:11]
	global_load_dword v66, v[20:21], off nt
	global_load_dword v67, v[22:23], off nt
	global_load_dword v68, v[24:25], off nt
	global_load_dword v69, v[26:27], off nt
	global_load_dword v70, v[28:29], off nt
	global_load_dword v71, v[30:31], off nt
	global_load_dword v72, v[32:33], off nt
	global_load_dword v73, v[34:35], off nt
	global_load_dword v74, v[36:37], off nt
	global_load_dword v75, v[38:39], off nt
	global_load_dword v76, v[40:41], off nt
	global_load_dword v77, v[42:43], off nt
	global_load_dword v78, v[44:45], off nt
	global_load_dword v79, v[46:47], off nt
	global_load_dword v80, v[48:49], off nt
	global_load_dword v81, v[50:51], off nt
	s_add_i32 s7, s7, 16
	s_add_i32 s6, s6, 16
	s_add_i32 s26, s26, -16
	v_mad_u64_u32 v[20:21], s[28:29], v19, s9, v[2:3]
	s_cmp_lg_u32 s26, 0
	v_mad_u64_u32 v[22:23], s[28:29], v9, s9, v[2:3]
	v_mad_u64_u32 v[24:25], s[28:29], v53, s9, v[2:3]
	v_mad_u64_u32 v[26:27], s[28:29], v52, s9, v[2:3]
	v_mad_u64_u32 v[28:29], s[28:29], v55, s9, v[2:3]
	v_mad_u64_u32 v[30:31], s[28:29], v54, s9, v[2:3]
	v_mad_u64_u32 v[32:33], s[28:29], v57, s9, v[2:3]
	v_mad_u64_u32 v[34:35], s[28:29], v56, s9, v[2:3]
	v_mad_u64_u32 v[36:37], s[28:29], v59, s9, v[2:3]
	v_mad_u64_u32 v[38:39], s[28:29], v58, s9, v[2:3]
	v_mad_u64_u32 v[40:41], s[28:29], v61, s9, v[2:3]
	v_mad_u64_u32 v[42:43], s[28:29], v60, s9, v[2:3]
	v_mad_u64_u32 v[44:45], s[28:29], v63, s9, v[2:3]
	v_mad_u64_u32 v[46:47], s[28:29], v62, s9, v[2:3]
	v_mad_u64_u32 v[48:49], s[28:29], v65, s9, v[2:3]
	v_mad_u64_u32 v[50:51], s[28:29], v64, s9, v[2:3]
	s_waitcnt vmcnt(15)
	ds_write_b32 v20, v66
	s_waitcnt vmcnt(14)
	ds_write_b32 v22, v67
	s_waitcnt vmcnt(13)
	ds_write_b32 v24, v68
	s_waitcnt vmcnt(12)
	ds_write_b32 v26, v69
	s_waitcnt vmcnt(11)
	ds_write_b32 v28, v70
	s_waitcnt vmcnt(10)
	ds_write_b32 v30, v71
	s_waitcnt vmcnt(9)
	ds_write_b32 v32, v72
	s_waitcnt vmcnt(8)
	ds_write_b32 v34, v73
	s_waitcnt vmcnt(7)
	ds_write_b32 v36, v74
	s_waitcnt vmcnt(6)
	ds_write_b32 v38, v75
	s_waitcnt vmcnt(5)
	ds_write_b32 v40, v76
	s_waitcnt vmcnt(4)
	ds_write_b32 v42, v77
	s_waitcnt vmcnt(3)
	ds_write_b32 v44, v78
	s_waitcnt vmcnt(2)
	ds_write_b32 v46, v79
	s_waitcnt vmcnt(1)
	ds_write_b32 v48, v80
	s_waitcnt vmcnt(0)
	ds_write_b32 v50, v81
	s_cbranch_scc1 .LBB0_592
	s_waitcnt lgkmcnt(0)
	ds_read2_b32 v[20:21], v14 offset0:33 offset1:41
	ds_read2_b32 v[22:23], v14 offset1:8
	ds_read2_b32 v[24:25], v14 offset0:66 offset1:74
	ds_read2_b32 v[26:27], v14 offset0:99 offset1:107
	ds_read2_b32 v[28:29], v14 offset0:132 offset1:140
	ds_read2_b32 v[30:31], v14 offset0:165 offset1:173
	ds_read2_b32 v[32:33], v14 offset0:198 offset1:206
	ds_read2_b32 v[34:35], v14 offset0:231 offset1:239
	v_add_u32_e32 v38, v18, v13
	v_ashrrev_i32_e32 v9, 31, v8
	v_ashrrev_i32_e32 v39, 31, v38
	v_lshl_add_u64 v[36:37], v[8:9], 1, v[6:7]
	v_lshlrev_b64 v[38:39], 12, v[38:39]
	s_waitcnt lgkmcnt(6)
	v_cvt_pk_bf16_f32 v8, v22, v20
	s_waitcnt lgkmcnt(4)
	v_cvt_pk_bf16_f32 v9, v24, v26
	s_waitcnt lgkmcnt(2)
	v_cvt_pk_bf16_f32 v10, v28, v30
	s_waitcnt lgkmcnt(0)
	v_cvt_pk_bf16_f32 v11, v32, v34
	v_lshl_add_u64 v[38:39], v[36:37], 0, v[38:39]
	v_add_u32_e32 v20, v18, v15
	global_store_dwordx4 v[38:39], v[8:11], off
	v_add_u32_e32 v12, s8, v12
	v_cmp_lt_i32_e32 vcc, s15, v12
	v_cvt_pk_bf16_f32 v8, v23, v21
	v_ashrrev_i32_e32 v21, 31, v20
	v_cvt_pk_bf16_f32 v9, v25, v27
	v_cvt_pk_bf16_f32 v10, v29, v31
	v_cvt_pk_bf16_f32 v11, v33, v35
	v_lshlrev_b64 v[20:21], 12, v[20:21]
	ds_read2_b32 v[22:23], v14 offset0:49 offset1:57
	ds_read2_b32 v[24:25], v14 offset0:16 offset1:24
	ds_read2_b32 v[26:27], v14 offset0:82 offset1:90
	ds_read2_b32 v[28:29], v14 offset0:115 offset1:123
	ds_read2_b32 v[30:31], v14 offset0:148 offset1:156
	ds_read2_b32 v[32:33], v14 offset0:181 offset1:189
	ds_read2_b32 v[34:35], v14 offset0:214 offset1:222
	ds_read2_b32 v[38:39], v14 offset0:247 offset1:255
	v_lshl_add_u64 v[20:21], v[36:37], 0, v[20:21]
	global_store_dwordx4 v[20:21], v[8:11], off
	v_add_u32_e32 v20, v18, v16
	v_ashrrev_i32_e32 v21, 31, v20
	v_add_u32_e32 v18, v18, v17
	v_lshlrev_b64 v[20:21], 12, v[20:21]
	v_ashrrev_i32_e32 v19, 31, v18
	s_waitcnt lgkmcnt(6)
	v_cvt_pk_bf16_f32 v8, v24, v22
	s_waitcnt lgkmcnt(4)
	v_cvt_pk_bf16_f32 v9, v26, v28
	s_waitcnt lgkmcnt(2)
	v_cvt_pk_bf16_f32 v10, v30, v32
	s_waitcnt lgkmcnt(0)
	v_cvt_pk_bf16_f32 v11, v34, v38
	v_lshl_add_u64 v[20:21], v[36:37], 0, v[20:21]
	v_lshlrev_b64 v[18:19], 12, v[18:19]
	global_store_dwordx4 v[20:21], v[8:11], off
	v_lshl_add_u64 v[18:19], v[36:37], 0, v[18:19]
	s_or_b64 s[4:5], vcc, s[4:5]
	v_cvt_pk_bf16_f32 v8, v25, v23
	v_cvt_pk_bf16_f32 v9, v27, v29
	v_cvt_pk_bf16_f32 v10, v31, v33
	v_cvt_pk_bf16_f32 v11, v35, v39
	global_store_dwordx4 v[18:19], v[8:11], off
	s_waitcnt lgkmcnt(0)
	s_andn2_b64 exec, exec, s[4:5]
	s_cbranch_execnz .LBB0_589

.LBB0_905:
	s_lshl_b32 s16, s15, 1
	s_lshl_b32 s17, s14, 1
	v_or_b32_e32 v11, s16, v1
	v_or_b32_e32 v13, s17, v2
	s_add_i32 s18, s16, 4
	s_add_i32 s19, s17, 4
	s_add_i32 s26, s16, 8
	s_add_i32 s27, s17, 8
	s_add_i32 s28, s16, 12
	s_add_i32 s29, s17, 12
	s_add_i32 s30, s16, 16
	s_add_i32 s31, s17, 16
	s_add_i32 s33, s16, 20
	s_add_i32 s35, s17, 20
	s_add_i32 s52, s16, 24
	s_add_i32 s53, s17, 24
	s_add_i32 s16, s16, 28
	s_add_i32 s17, s17, 28
	v_add_u32_e32 v15, v11, v3
	v_add_u32_e32 v22, v13, v10
	v_or_b32_e32 v54, s18, v1
	v_or_b32_e32 v55, s19, v2
	v_or_b32_e32 v56, s26, v1
	v_or_b32_e32 v57, s27, v2
	v_or_b32_e32 v58, s28, v1
	v_or_b32_e32 v59, s29, v2
	v_or_b32_e32 v60, s30, v1
	v_or_b32_e32 v61, s31, v2
	v_or_b32_e32 v62, s33, v1
	v_or_b32_e32 v63, s35, v2
	v_or_b32_e32 v64, s52, v1
	v_or_b32_e32 v65, s53, v2
	v_or_b32_e32 v66, s16, v1
	v_or_b32_e32 v67, s17, v2
	v_mad_i64_i32 v[22:23], s[16:17], v22, s10, v[16:17]
	v_mad_i64_i32 v[24:25], s[16:17], v15, s10, v[16:17]
	v_add_u32_e32 v15, v54, v3
	v_add_u32_e32 v26, v55, v10
	v_add_u32_e32 v32, v56, v3
	v_add_u32_e32 v30, v57, v10
	v_add_u32_e32 v36, v58, v3
	v_add_u32_e32 v34, v59, v10
	v_add_u32_e32 v40, v60, v3
	v_add_u32_e32 v38, v61, v10
	v_add_u32_e32 v44, v62, v3
	v_add_u32_e32 v42, v63, v10
	v_add_u32_e32 v48, v64, v3
	v_add_u32_e32 v46, v65, v10
	v_add_u32_e32 v52, v66, v3
	v_add_u32_e32 v50, v67, v10
	v_mad_i64_i32 v[26:27], s[16:17], v26, s10, v[16:17]
	v_mad_i64_i32 v[28:29], s[16:17], v15, s10, v[16:17]
	v_mad_i64_i32 v[30:31], s[16:17], v30, s10, v[16:17]
	v_mad_i64_i32 v[32:33], s[16:17], v32, s10, v[16:17]
	v_mad_i64_i32 v[34:35], s[16:17], v34, s10, v[16:17]
	v_mad_i64_i32 v[36:37], s[16:17], v36, s10, v[16:17]
	v_mad_i64_i32 v[38:39], s[16:17], v38, s10, v[16:17]
	v_mad_i64_i32 v[40:41], s[16:17], v40, s10, v[16:17]
	v_mad_i64_i32 v[42:43], s[16:17], v42, s10, v[16:17]
	v_mad_i64_i32 v[44:45], s[16:17], v44, s10, v[16:17]
	v_mad_i64_i32 v[46:47], s[16:17], v46, s10, v[16:17]
	v_mad_i64_i32 v[48:49], s[16:17], v48, s10, v[16:17]
	v_mad_i64_i32 v[50:51], s[16:17], v50, s10, v[16:17]
	v_mad_i64_i32 v[52:53], s[16:17], v52, s10, v[16:17]
	global_load_dword v15, v[22:23], off nt
	global_load_dword v68, v[24:25], off nt
	global_load_dword v69, v[26:27], off nt
	global_load_dword v70, v[28:29], off nt
	global_load_dword v71, v[30:31], off nt
	global_load_dword v72, v[32:33], off nt
	global_load_dword v73, v[34:35], off nt
	global_load_dword v74, v[36:37], off nt
	global_load_dword v75, v[38:39], off nt
	global_load_dword v76, v[40:41], off nt
	global_load_dword v77, v[42:43], off nt
	global_load_dword v78, v[44:45], off nt
	global_load_dword v79, v[46:47], off nt
	global_load_dword v80, v[48:49], off nt
	global_load_dword v81, v[50:51], off nt
	global_load_dword v82, v[52:53], off nt
	s_add_i32 s14, s14, 16
	s_add_i32 s15, s15, 16
	s_add_i32 s13, s13, -16
	v_mad_u64_u32 v[22:23], s[16:17], v13, s5, v[4:5]
	s_cmp_lg_u32 s13, 0
	v_mad_u64_u32 v[24:25], s[16:17], v11, s5, v[4:5]
	v_mad_u64_u32 v[26:27], s[16:17], v55, s5, v[4:5]
	v_mad_u64_u32 v[28:29], s[16:17], v54, s5, v[4:5]
	v_mad_u64_u32 v[30:31], s[16:17], v57, s5, v[4:5]
	v_mad_u64_u32 v[32:33], s[16:17], v56, s5, v[4:5]
	v_mad_u64_u32 v[34:35], s[16:17], v59, s5, v[4:5]
	v_mad_u64_u32 v[36:37], s[16:17], v58, s5, v[4:5]
	v_mad_u64_u32 v[38:39], s[16:17], v61, s5, v[4:5]
	v_mad_u64_u32 v[40:41], s[16:17], v60, s5, v[4:5]
	v_mad_u64_u32 v[42:43], s[16:17], v63, s5, v[4:5]
	v_mad_u64_u32 v[44:45], s[16:17], v62, s5, v[4:5]
	v_mad_u64_u32 v[46:47], s[16:17], v65, s5, v[4:5]
	v_mad_u64_u32 v[48:49], s[16:17], v64, s5, v[4:5]
	v_mad_u64_u32 v[50:51], s[16:17], v67, s5, v[4:5]
	v_mad_u64_u32 v[52:53], s[16:17], v66, s5, v[4:5]
	s_waitcnt vmcnt(15)
	ds_write_b32 v22, v15
	s_waitcnt vmcnt(14)
	ds_write_b32 v24, v68
	s_waitcnt vmcnt(13)
	ds_write_b32 v26, v69
	s_waitcnt vmcnt(12)
	ds_write_b32 v28, v70
	s_waitcnt vmcnt(11)
	ds_write_b32 v30, v71
	s_waitcnt vmcnt(10)
	ds_write_b32 v32, v72
	s_waitcnt vmcnt(9)
	ds_write_b32 v34, v73
	s_waitcnt vmcnt(8)
	ds_write_b32 v36, v74
	s_waitcnt vmcnt(7)
	ds_write_b32 v38, v75
	s_waitcnt vmcnt(6)
	ds_write_b32 v40, v76
	s_waitcnt vmcnt(5)
	ds_write_b32 v42, v77
	s_waitcnt vmcnt(4)
	ds_write_b32 v44, v78
	s_waitcnt vmcnt(3)
	ds_write_b32 v46, v79
	s_waitcnt vmcnt(2)
	ds_write_b32 v48, v80
	s_waitcnt vmcnt(1)
	ds_write_b32 v50, v81
	s_waitcnt vmcnt(0)
	ds_write_b32 v52, v82
	s_cbranch_scc1 .LBB0_905
	v_lshlrev_b32_e32 v3, 6, v12
	s_waitcnt lgkmcnt(0)
	v_and_b32_e32 v3, 0xffffff00, v3
	v_and_b32_e32 v11, 0x60, v14
	ds_read2_b32 v[14:15], v18 offset0:33 offset1:41
	ds_read2_b32 v[16:17], v18 offset1:8
	ds_read2_b32 v[22:23], v18 offset0:66 offset1:74
	ds_read2_b32 v[24:25], v18 offset0:99 offset1:107
	ds_read2_b32 v[26:27], v18 offset0:132 offset1:140
	ds_read2_b32 v[28:29], v18 offset0:165 offset1:173
	ds_read2_b32 v[30:31], v18 offset0:198 offset1:206
	ds_read2_b32 v[32:33], v18 offset0:231 offset1:239
	v_or3_b32 v3, v11, v3, s11
	v_or_b32_e32 v36, v3, v5
	v_ashrrev_i32_e32 v11, 31, v10
	v_ashrrev_i32_e32 v37, 31, v36
	v_lshl_add_u64 v[34:35], v[10:11], 1, v[8:9]
	v_lshlrev_b64 v[36:37], 12, v[36:37]
	s_waitcnt lgkmcnt(6)
	v_cvt_pk_bf16_f32 v10, v16, v14
	s_waitcnt lgkmcnt(4)
	v_cvt_pk_bf16_f32 v11, v22, v24
	s_waitcnt lgkmcnt(2)
	v_cvt_pk_bf16_f32 v12, v26, v28
	s_waitcnt lgkmcnt(0)
	v_cvt_pk_bf16_f32 v13, v30, v32
	v_lshl_add_u64 v[36:37], v[34:35], 0, v[36:37]
	v_or_b32_e32 v14, v3, v19
	global_store_dwordx4 v[36:37], v[10:13], off
	v_add_u32_e32 v0, s4, v0
	v_cmp_lt_i32_e32 vcc, s12, v0
	v_cvt_pk_bf16_f32 v10, v17, v15
	v_ashrrev_i32_e32 v15, 31, v14
	v_cvt_pk_bf16_f32 v11, v23, v25
	v_cvt_pk_bf16_f32 v12, v27, v29
	v_cvt_pk_bf16_f32 v13, v31, v33
	v_lshlrev_b64 v[14:15], 12, v[14:15]
	ds_read2_b32 v[16:17], v18 offset0:49 offset1:57
	ds_read2_b32 v[22:23], v18 offset0:16 offset1:24
	ds_read2_b32 v[24:25], v18 offset0:82 offset1:90
	ds_read2_b32 v[26:27], v18 offset0:115 offset1:123
	ds_read2_b32 v[28:29], v18 offset0:148 offset1:156
	ds_read2_b32 v[30:31], v18 offset0:181 offset1:189
	ds_read2_b32 v[32:33], v18 offset0:214 offset1:222
	ds_read2_b32 v[36:37], v18 offset0:247 offset1:255
	v_lshl_add_u64 v[14:15], v[34:35], 0, v[14:15]
	global_store_dwordx4 v[14:15], v[10:13], off
	v_or_b32_e32 v14, v3, v20
	v_ashrrev_i32_e32 v15, 31, v14
	v_lshlrev_b64 v[14:15], 12, v[14:15]
	s_waitcnt lgkmcnt(6)
	v_cvt_pk_bf16_f32 v10, v22, v16
	s_waitcnt lgkmcnt(4)
	v_cvt_pk_bf16_f32 v11, v24, v26
	s_waitcnt lgkmcnt(2)
	v_cvt_pk_bf16_f32 v12, v28, v30
	s_waitcnt lgkmcnt(0)
	v_cvt_pk_bf16_f32 v13, v32, v36
	v_lshl_add_u64 v[14:15], v[34:35], 0, v[14:15]
	global_store_dwordx4 v[14:15], v[10:13], off
	v_or_b32_e32 v14, v3, v21
	v_ashrrev_i32_e32 v15, 31, v14
	v_lshlrev_b64 v[14:15], 12, v[14:15]
	v_cvt_pk_bf16_f32 v10, v23, v17
	v_cvt_pk_bf16_f32 v11, v25, v27
	v_cvt_pk_bf16_f32 v12, v29, v31
	v_cvt_pk_bf16_f32 v13, v33, v37
	v_lshl_add_u64 v[14:15], v[34:35], 0, v[14:15]
	global_store_dwordx4 v[14:15], v[10:13], off
	s_waitcnt lgkmcnt(0)
	s_or_b64 s[2:3], vcc, s[2:3]
	s_andn2_b64 exec, exec, s[2:3]
	s_cbranch_execnz .LBB0_904

.LBB0_1033:
	v_bfe_u32 v0, v7, 6, 7
	v_lshrrev_b32_e32 v8, 1, v7
	v_and_or_b32 v0, v8, s11, v0
	v_mul_u32_u24_e32 v0, 0x2e00, v0
	v_cmp_gt_u32_e32 vcc, s12, v7
	v_lshlrev_b32_e32 v0, 1, v0
	v_and_b32_e32 v12, 0xfc, v2
	v_lshl_add_u64 v[8:9], s[2:3], 0, v[0:1]
	v_cndmask_b32_e32 v0, v3, v4, vcc
	v_lshl_add_u64 v[8:9], v[8:9], 0, v[0:1]
	v_lshlrev_b32_e32 v0, 1, v12
	v_lshl_add_u64 v[8:9], v[8:9], 0, v[0:1]
	v_add_co_u32_e64 v8, s[4:5], s13, v8
	v_lshlrev_b32_e32 v13, 4, v7
	s_nop 0
	v_addc_co_u32_e64 v9, s[4:5], 0, v9, s[4:5]
	global_load_dwordx2 v[10:11], v[8:9], off nt
	v_cndmask_b32_e32 v0, v5, v6, vcc
	v_add_u32_e32 v7, s30, v7
	v_lshl_add_u64 v[8:9], s[48:49], 0, v[0:1]
	v_and_b32_e32 v0, 0x3fc00, v13
	v_cmp_lt_i32_e64 s[4:5], s14, v7
	v_lshl_add_u64 v[8:9], v[8:9], 0, v[0:1]
	v_lshlrev_b32_e32 v0, 2, v12
	v_add_u32_e32 v2, s10, v2
	s_or_b64 s[8:9], s[4:5], s[8:9]
	v_lshl_add_u64 v[12:13], v[8:9], 0, v[0:1]
	s_waitcnt vmcnt(0)
	v_lshlrev_b32_e32 v8, 16, v10
	v_and_b32_e32 v9, 0xffff0000, v10
	v_lshlrev_b32_e32 v10, 16, v11
	v_and_b32_e32 v11, 0xffff0000, v11
	global_store_dwordx4 v[12:13], v[8:11], off nt
	s_andn2_b64 exec, exec, s[8:9]
	s_cbranch_execnz .LBB0_1033

.LBB0_1037:
	v_bfe_u32 v40, v39, 6, 7
	v_and_b32_e32 v41, 0xfc, v34
	v_bfe_u32 v42, v39, 13, 7
	v_cmp_lt_u32_e32 vcc, s63, v40
	s_and_saveexec_b64 s[4:5], vcc
	s_xor_b64 s[4:5], exec, s[4:5]
	s_cbranch_execz .LBB0_1039
	v_lshlrev_b32_e32 v28, 3, v42
	v_add3_u32 v28, v40, v28, s64
	v_mul_u32_u24_e32 v32, 0x5c00, v28
	v_cmp_gt_u32_e32 vcc, s65, v39
	v_lshl_add_u64 v[28:29], s[2:3], 0, v[32:33]
	s_nop 0
	v_cndmask_b32_e32 v32, v35, v36, vcc
	v_lshl_add_u64 v[28:29], v[28:29], 0, v[32:33]
	v_lshlrev_b32_e32 v32, 1, v41
	v_lshl_add_u64 v[28:29], v[28:29], 0, v[32:33]
	global_load_dwordx2 v[30:31], v[28:29], off nt
	s_waitcnt vmcnt(0)
	v_lshlrev_b32_e32 v28, 16, v30
	v_and_b32_e32 v29, 0xffff0000, v30
	v_lshlrev_b32_e32 v30, 16, v31
	v_and_b32_e32 v31, 0xffff0000, v31
.LBB0_1039:
	s_or_saveexec_b64 s[4:5], s[4:5]
	v_lshlrev_b32_e32 v32, 2, v41
	s_xor_b64 exec, exec, s[4:5]
	s_cbranch_execz .LBB0_1041
	v_mov_b32_e32 v28, s23
	v_mov_b32_e32 v29, s21
	v_cmp_gt_u32_e32 vcc, s65, v39
	v_mov_b32_e32 v30, s20
	v_mov_b32_e32 v31, v33
	v_cndmask_b32_e32 v29, v28, v29, vcc
	v_mov_b32_e32 v28, s22
	v_cndmask_b32_e32 v28, v28, v30, vcc
	v_lshlrev_b32_e32 v30, 10, v40
	v_lshl_or_b32 v30, v42, 17, v30
	v_lshl_add_u64 v[28:29], v[28:29], 0, v[30:31]
	v_lshl_add_u64 v[28:29], v[28:29], 0, v[32:33]
	v_add_co_u32_e32 v28, vcc, 0x2000, v28
	s_nop 1
	v_addc_co_u32_e32 v29, vcc, 0, v29, vcc
	global_load_dwordx4 v[28:31], v[28:29], off nt
.LBB0_1041:
	s_or_b64 exec, exec, s[4:5]
	v_add_u32_e32 v40, s30, v39
	v_cmp_gt_i32_e64 s[4:5], s31, v40
	s_and_saveexec_b64 s[6:7], s[4:5]
	s_cbranch_execz .LBB0_1047
	v_bfe_u32 v42, v40, 6, 7
	v_bfe_u32 v43, v40, 13, 7
	v_cmp_lt_u32_e32 vcc, s63, v42
	s_and_saveexec_b64 s[8:9], vcc
	s_xor_b64 s[8:9], exec, s[8:9]
	s_cbranch_execz .LBB0_1044
	v_lshlrev_b32_e32 v0, 3, v43
	v_add3_u32 v0, v42, v0, s64
	v_mul_u32_u24_e32 v0, 0x5c00, v0
	v_mov_b32_e32 v1, v33
	v_cmp_gt_u32_e32 vcc, s65, v40
	v_lshl_add_u64 v[0:1], s[2:3], 0, v[0:1]
	v_mov_b32_e32 v3, v33
	v_cndmask_b32_e32 v2, v35, v36, vcc
	v_lshl_add_u64 v[0:1], v[0:1], 0, v[2:3]
	v_lshlrev_b32_e32 v2, 1, v41
	v_lshl_add_u64 v[0:1], v[0:1], 0, v[2:3]
	global_load_dwordx2 v[2:3], v[0:1], off nt
	s_waitcnt vmcnt(0)
	v_lshlrev_b32_e32 v0, 16, v2
	v_and_b32_e32 v1, 0xffff0000, v2
	v_lshlrev_b32_e32 v2, 16, v3
	v_and_b32_e32 v3, 0xffff0000, v3
.LBB0_1044:
	s_andn2_saveexec_b64 s[8:9], s[8:9]
	s_cbranch_execz .LBB0_1046
	v_mov_b32_e32 v0, s23
	v_mov_b32_e32 v1, s21
	v_cmp_gt_u32_e32 vcc, s65, v40
	v_mov_b32_e32 v2, s20
	v_mov_b32_e32 v3, v33
	v_cndmask_b32_e32 v1, v0, v1, vcc
	v_mov_b32_e32 v0, s22
	v_cndmask_b32_e32 v0, v0, v2, vcc
	v_lshlrev_b32_e32 v2, 10, v42
	v_lshl_or_b32 v2, v43, 17, v2
	v_lshl_add_u64 v[0:1], v[0:1], 0, v[2:3]
	v_lshl_add_u64 v[0:1], v[0:1], 0, v[32:33]
	v_add_co_u32_e32 v0, vcc, 0x2000, v0
	s_nop 1
	v_addc_co_u32_e32 v1, vcc, 0, v1, vcc
	global_load_dwordx4 v[0:3], v[0:1], off nt

.LBB0_1047:
	s_or_b64 exec, exec, s[6:7]
	v_add_u32_e32 v42, s33, v39
	v_cmp_gt_i32_e64 s[6:7], s31, v42
	s_and_saveexec_b64 s[8:9], s[6:7]
	s_cbranch_execz .LBB0_1053
	v_bfe_u32 v43, v42, 6, 7
	v_bfe_u32 v44, v42, 13, 7
	v_cmp_lt_u32_e32 vcc, s63, v43
	s_and_saveexec_b64 s[10:11], vcc
	s_xor_b64 s[10:11], exec, s[10:11]
	s_cbranch_execz .LBB0_1050
	v_lshlrev_b32_e32 v4, 3, v44
	v_add3_u32 v4, v43, v4, s64
	v_mul_u32_u24_e32 v4, 0x5c00, v4
	v_mov_b32_e32 v5, v33
	v_cmp_gt_u32_e32 vcc, s65, v42
	v_lshl_add_u64 v[4:5], s[2:3], 0, v[4:5]
	v_mov_b32_e32 v7, v33
	v_cndmask_b32_e32 v6, v35, v36, vcc
	v_lshl_add_u64 v[4:5], v[4:5], 0, v[6:7]
	v_lshlrev_b32_e32 v6, 1, v41
	v_lshl_add_u64 v[4:5], v[4:5], 0, v[6:7]
	global_load_dwordx2 v[6:7], v[4:5], off nt
	s_waitcnt vmcnt(0)
	v_lshlrev_b32_e32 v4, 16, v6
	v_and_b32_e32 v5, 0xffff0000, v6
	v_lshlrev_b32_e32 v6, 16, v7
	v_and_b32_e32 v7, 0xffff0000, v7
.LBB0_1050:
	s_andn2_saveexec_b64 s[10:11], s[10:11]
	s_cbranch_execz .LBB0_1052
	v_mov_b32_e32 v4, s23
	v_mov_b32_e32 v5, s21
	v_cmp_gt_u32_e32 vcc, s65, v42
	v_mov_b32_e32 v6, s20
	v_mov_b32_e32 v7, v33
	v_cndmask_b32_e32 v5, v4, v5, vcc
	v_mov_b32_e32 v4, s22
	v_cndmask_b32_e32 v4, v4, v6, vcc
	v_lshlrev_b32_e32 v6, 10, v43
	v_lshl_or_b32 v6, v44, 17, v6
	v_lshl_add_u64 v[4:5], v[4:5], 0, v[6:7]
	v_lshl_add_u64 v[4:5], v[4:5], 0, v[32:33]
	v_add_co_u32_e32 v4, vcc, 0x2000, v4
	s_nop 1
	v_addc_co_u32_e32 v5, vcc, 0, v5, vcc
	global_load_dwordx4 v[4:7], v[4:5], off nt

.LBB0_1053:
	s_or_b64 exec, exec, s[8:9]
	v_add_u32_e32 v43, s53, v39
	v_cmp_gt_i32_e64 s[8:9], s31, v43
	s_and_saveexec_b64 s[10:11], s[8:9]
	s_cbranch_execz .LBB0_1059
	v_bfe_u32 v44, v43, 6, 7
	v_bfe_u32 v45, v43, 13, 7
	v_cmp_lt_u32_e32 vcc, s63, v44
	s_and_saveexec_b64 s[12:13], vcc
	s_xor_b64 s[12:13], exec, s[12:13]
	s_cbranch_execz .LBB0_1056
	v_lshlrev_b32_e32 v8, 3, v45
	v_add3_u32 v8, v44, v8, s64
	v_mul_u32_u24_e32 v8, 0x5c00, v8
	v_mov_b32_e32 v9, v33
	v_cmp_gt_u32_e32 vcc, s65, v43
	v_lshl_add_u64 v[8:9], s[2:3], 0, v[8:9]
	v_mov_b32_e32 v11, v33
	v_cndmask_b32_e32 v10, v35, v36, vcc
	v_lshl_add_u64 v[8:9], v[8:9], 0, v[10:11]
	v_lshlrev_b32_e32 v10, 1, v41
	v_lshl_add_u64 v[8:9], v[8:9], 0, v[10:11]
	global_load_dwordx2 v[10:11], v[8:9], off nt
	s_waitcnt vmcnt(0)
	v_lshlrev_b32_e32 v8, 16, v10
	v_and_b32_e32 v9, 0xffff0000, v10
	v_lshlrev_b32_e32 v10, 16, v11
	v_and_b32_e32 v11, 0xffff0000, v11
.LBB0_1056:
	s_andn2_saveexec_b64 s[12:13], s[12:13]
	s_cbranch_execz .LBB0_1058
	v_mov_b32_e32 v8, s23
	v_mov_b32_e32 v9, s21
	v_cmp_gt_u32_e32 vcc, s65, v43
	v_mov_b32_e32 v10, s20
	v_mov_b32_e32 v11, v33
	v_cndmask_b32_e32 v9, v8, v9, vcc
	v_mov_b32_e32 v8, s22
	v_cndmask_b32_e32 v8, v8, v10, vcc
	v_lshlrev_b32_e32 v10, 10, v44
	v_lshl_or_b32 v10, v45, 17, v10
	v_lshl_add_u64 v[8:9], v[8:9], 0, v[10:11]
	v_lshl_add_u64 v[8:9], v[8:9], 0, v[32:33]
	v_add_co_u32_e32 v8, vcc, 0x2000, v8
	s_nop 1
	v_addc_co_u32_e32 v9, vcc, 0, v9, vcc
	global_load_dwordx4 v[8:11], v[8:9], off nt

.LBB0_1059:
	s_or_b64 exec, exec, s[10:11]
	v_add_u32_e32 v44, s55, v39
	v_cmp_gt_i32_e64 s[10:11], s31, v44
	s_and_saveexec_b64 s[12:13], s[10:11]
	s_cbranch_execz .LBB0_1065
	v_bfe_u32 v45, v44, 6, 7
	v_bfe_u32 v46, v44, 13, 7
	v_cmp_lt_u32_e32 vcc, s63, v45
	s_and_saveexec_b64 s[14:15], vcc
	s_xor_b64 s[14:15], exec, s[14:15]
	s_cbranch_execz .LBB0_1062
	v_lshlrev_b32_e32 v12, 3, v46
	v_add3_u32 v12, v45, v12, s64
	v_mul_u32_u24_e32 v12, 0x5c00, v12
	v_mov_b32_e32 v13, v33
	v_cmp_gt_u32_e32 vcc, s65, v44
	v_lshl_add_u64 v[12:13], s[2:3], 0, v[12:13]
	v_mov_b32_e32 v15, v33
	v_cndmask_b32_e32 v14, v35, v36, vcc
	v_lshl_add_u64 v[12:13], v[12:13], 0, v[14:15]
	v_lshlrev_b32_e32 v14, 1, v41
	v_lshl_add_u64 v[12:13], v[12:13], 0, v[14:15]
	global_load_dwordx2 v[14:15], v[12:13], off nt
	s_waitcnt vmcnt(0)
	v_lshlrev_b32_e32 v12, 16, v14
	v_and_b32_e32 v13, 0xffff0000, v14
	v_lshlrev_b32_e32 v14, 16, v15
	v_and_b32_e32 v15, 0xffff0000, v15
.LBB0_1062:
	s_andn2_saveexec_b64 s[14:15], s[14:15]
	s_cbranch_execz .LBB0_1064
	v_mov_b32_e32 v12, s23
	v_mov_b32_e32 v13, s21
	v_cmp_gt_u32_e32 vcc, s65, v44
	v_mov_b32_e32 v14, s20
	v_mov_b32_e32 v15, v33
	v_cndmask_b32_e32 v13, v12, v13, vcc
	v_mov_b32_e32 v12, s22
	v_cndmask_b32_e32 v12, v12, v14, vcc
	v_lshlrev_b32_e32 v14, 10, v45
	v_lshl_or_b32 v14, v46, 17, v14
	v_lshl_add_u64 v[12:13], v[12:13], 0, v[14:15]
	v_lshl_add_u64 v[12:13], v[12:13], 0, v[32:33]
	v_add_co_u32_e32 v12, vcc, 0x2000, v12
	s_nop 1
	v_addc_co_u32_e32 v13, vcc, 0, v13, vcc
	global_load_dwordx4 v[12:15], v[12:13], off nt

.LBB0_1065:
	s_or_b64 exec, exec, s[12:13]
	v_add_u32_e32 v45, s57, v39
	v_cmp_gt_i32_e64 s[12:13], s31, v45
	s_and_saveexec_b64 s[14:15], s[12:13]
	s_cbranch_execz .LBB0_1071
	v_bfe_u32 v46, v45, 6, 7
	v_bfe_u32 v47, v45, 13, 7
	v_cmp_lt_u32_e32 vcc, s63, v46
	s_and_saveexec_b64 s[16:17], vcc
	s_xor_b64 s[16:17], exec, s[16:17]
	s_cbranch_execz .LBB0_1068
	v_lshlrev_b32_e32 v16, 3, v47
	v_add3_u32 v16, v46, v16, s64
	v_mul_u32_u24_e32 v16, 0x5c00, v16
	v_mov_b32_e32 v17, v33
	v_cmp_gt_u32_e32 vcc, s65, v45
	v_lshl_add_u64 v[16:17], s[2:3], 0, v[16:17]
	v_mov_b32_e32 v19, v33
	v_cndmask_b32_e32 v18, v35, v36, vcc
	v_lshl_add_u64 v[16:17], v[16:17], 0, v[18:19]
	v_lshlrev_b32_e32 v18, 1, v41
	v_lshl_add_u64 v[16:17], v[16:17], 0, v[18:19]
	global_load_dwordx2 v[18:19], v[16:17], off nt
	s_waitcnt vmcnt(0)
	v_lshlrev_b32_e32 v16, 16, v18
	v_and_b32_e32 v17, 0xffff0000, v18
	v_lshlrev_b32_e32 v18, 16, v19
	v_and_b32_e32 v19, 0xffff0000, v19
.LBB0_1068:
	s_andn2_saveexec_b64 s[16:17], s[16:17]
	s_cbranch_execz .LBB0_1070
	v_mov_b32_e32 v16, s23
	v_mov_b32_e32 v17, s21
	v_cmp_gt_u32_e32 vcc, s65, v45
	v_mov_b32_e32 v18, s20
	v_mov_b32_e32 v19, v33
	v_cndmask_b32_e32 v17, v16, v17, vcc
	v_mov_b32_e32 v16, s22
	v_cndmask_b32_e32 v16, v16, v18, vcc
	v_lshlrev_b32_e32 v18, 10, v46
	v_lshl_or_b32 v18, v47, 17, v18
	v_lshl_add_u64 v[16:17], v[16:17], 0, v[18:19]
	v_lshl_add_u64 v[16:17], v[16:17], 0, v[32:33]
	v_add_co_u32_e32 v16, vcc, 0x2000, v16
	s_nop 1
	v_addc_co_u32_e32 v17, vcc, 0, v17, vcc
	global_load_dwordx4 v[16:19], v[16:17], off nt

.LBB0_1071:
	s_or_b64 exec, exec, s[14:15]
	v_add_u32_e32 v46, s59, v39
	v_cmp_gt_i32_e64 s[14:15], s31, v46
	s_and_saveexec_b64 s[16:17], s[14:15]
	s_cbranch_execz .LBB0_1077
	v_bfe_u32 v47, v46, 6, 7
	v_bfe_u32 v48, v46, 13, 7
	v_cmp_lt_u32_e32 vcc, s63, v47
	s_and_saveexec_b64 s[26:27], vcc
	s_xor_b64 s[26:27], exec, s[26:27]
	s_cbranch_execz .LBB0_1074
	v_lshlrev_b32_e32 v20, 3, v48
	v_add3_u32 v20, v47, v20, s64
	v_mul_u32_u24_e32 v20, 0x5c00, v20
	v_mov_b32_e32 v21, v33
	v_cmp_gt_u32_e32 vcc, s65, v46
	v_lshl_add_u64 v[20:21], s[2:3], 0, v[20:21]
	v_mov_b32_e32 v23, v33
	v_cndmask_b32_e32 v22, v35, v36, vcc
	v_lshl_add_u64 v[20:21], v[20:21], 0, v[22:23]
	v_lshlrev_b32_e32 v22, 1, v41
	v_lshl_add_u64 v[20:21], v[20:21], 0, v[22:23]
	global_load_dwordx2 v[22:23], v[20:21], off nt
	s_waitcnt vmcnt(0)
	v_lshlrev_b32_e32 v20, 16, v22
	v_and_b32_e32 v21, 0xffff0000, v22
	v_lshlrev_b32_e32 v22, 16, v23
	v_and_b32_e32 v23, 0xffff0000, v23
.LBB0_1074:
	s_andn2_saveexec_b64 s[26:27], s[26:27]
	s_cbranch_execz .LBB0_1076
	v_mov_b32_e32 v20, s23
	v_mov_b32_e32 v21, s21
	v_cmp_gt_u32_e32 vcc, s65, v46
	v_mov_b32_e32 v22, s20
	v_mov_b32_e32 v23, v33
	v_cndmask_b32_e32 v21, v20, v21, vcc
	v_mov_b32_e32 v20, s22
	v_cndmask_b32_e32 v20, v20, v22, vcc
	v_lshlrev_b32_e32 v22, 10, v47
	v_lshl_or_b32 v22, v48, 17, v22
	v_lshl_add_u64 v[20:21], v[20:21], 0, v[22:23]
	v_lshl_add_u64 v[20:21], v[20:21], 0, v[32:33]
	v_add_co_u32_e32 v20, vcc, 0x2000, v20
	s_nop 1
	v_addc_co_u32_e32 v21, vcc, 0, v21, vcc
	global_load_dwordx4 v[20:23], v[20:21], off nt

.LBB0_1077:
	s_or_b64 exec, exec, s[16:17]
	v_add_u32_e32 v47, s61, v39
	v_cmp_gt_i32_e64 s[16:17], s31, v47
	s_and_saveexec_b64 s[26:27], s[16:17]
	s_cbranch_execz .LBB0_1083
	v_bfe_u32 v48, v47, 6, 7
	v_bfe_u32 v49, v47, 13, 7
	v_cmp_lt_u32_e32 vcc, s63, v48
	s_and_saveexec_b64 s[28:29], vcc
	s_xor_b64 s[28:29], exec, s[28:29]
	s_cbranch_execz .LBB0_1080
	v_lshlrev_b32_e32 v24, 3, v49
	v_add3_u32 v24, v48, v24, s64
	v_mul_u32_u24_e32 v24, 0x5c00, v24
	v_mov_b32_e32 v25, v33
	v_cmp_gt_u32_e32 vcc, s65, v47
	v_lshl_add_u64 v[24:25], s[2:3], 0, v[24:25]
	v_mov_b32_e32 v27, v33
	v_cndmask_b32_e32 v26, v35, v36, vcc
	v_lshl_add_u64 v[24:25], v[24:25], 0, v[26:27]
	v_lshlrev_b32_e32 v26, 1, v41
	v_lshl_add_u64 v[24:25], v[24:25], 0, v[26:27]
	global_load_dwordx2 v[26:27], v[24:25], off nt
	s_waitcnt vmcnt(0)
	v_lshlrev_b32_e32 v24, 16, v26
	v_and_b32_e32 v25, 0xffff0000, v26
	v_lshlrev_b32_e32 v26, 16, v27
	v_and_b32_e32 v27, 0xffff0000, v27
.LBB0_1080:
	s_andn2_saveexec_b64 s[28:29], s[28:29]
	s_cbranch_execz .LBB0_1082
	v_mov_b32_e32 v24, s23
	v_mov_b32_e32 v25, s21
	v_cmp_gt_u32_e32 vcc, s65, v47
	v_mov_b32_e32 v26, s20
	v_mov_b32_e32 v27, v33
	v_cndmask_b32_e32 v25, v24, v25, vcc
	v_mov_b32_e32 v24, s22
	v_cndmask_b32_e32 v24, v24, v26, vcc
	v_lshlrev_b32_e32 v26, 10, v48
	v_lshl_or_b32 v26, v49, 17, v26
	v_lshl_add_u64 v[24:25], v[24:25], 0, v[26:27]
	v_lshl_add_u64 v[24:25], v[24:25], 0, v[32:33]
	v_add_co_u32_e32 v24, vcc, 0x2000, v24
	s_nop 1
	v_addc_co_u32_e32 v25, vcc, 0, v25, vcc
	global_load_dwordx4 v[24:27], v[24:25], off nt

.LBB0_1482:
	s_lshl_b32 s25, s22, 1
	s_lshl_b32 s26, s23, 1
	v_or_b32_e32 v11, s25, v1
	v_or_b32_e32 v17, s26, v4
	s_add_i32 s27, s25, 4
	s_add_i32 s28, s26, 4
	s_add_i32 s29, s25, 8
	s_add_i32 s30, s26, 8
	s_add_i32 s31, s25, 12
	s_add_i32 s52, s26, 12
	s_add_i32 s53, s25, 16
	s_add_i32 s57, s26, 16
	s_add_i32 s58, s25, 20
	s_add_i32 s59, s26, 20
	s_add_i32 s60, s25, 24
	s_add_i32 s61, s26, 24
	s_add_i32 s25, s25, 28
	s_add_i32 s26, s26, 28
	v_add_u32_e32 v25, v11, v3
	v_add_u32_e32 v28, v17, v16
	v_or_b32_e32 v87, s27, v1
	v_or_b32_e32 v89, s28, v4
	v_or_b32_e32 v90, s29, v1
	v_or_b32_e32 v91, s30, v4
	v_or_b32_e32 v92, s31, v1
	v_or_b32_e32 v93, s52, v4
	v_or_b32_e32 v94, s53, v1
	v_or_b32_e32 v95, s57, v4
	v_or_b32_e32 v96, s58, v1
	v_or_b32_e32 v97, s59, v4
	v_or_b32_e32 v98, s60, v1
	v_or_b32_e32 v99, s61, v4
	v_or_b32_e32 v100, s25, v1
	v_or_b32_e32 v101, s26, v4
	v_ashrrev_i32_e32 v33, 31, v28
	v_ashrrev_i32_e32 v31, 31, v25
	v_mad_u64_u32 v[26:27], s[26:27], v2, v25, 0
	v_mad_u64_u32 v[28:29], s[26:27], v0, v28, 0
	v_add_u32_e32 v25, v87, v3
	v_add_u32_e32 v36, v89, v16
	v_add_u32_e32 v38, v90, v3
	v_add_u32_e32 v40, v91, v16
	v_add_u32_e32 v42, v92, v3
	v_add_u32_e32 v44, v93, v16
	v_add_u32_e32 v46, v94, v3
	v_add_u32_e32 v48, v95, v16
	v_add_u32_e32 v50, v96, v3
	v_add_u32_e32 v52, v97, v16
	v_add_u32_e32 v54, v98, v3
	v_add_u32_e32 v56, v99, v16
	v_add_u32_e32 v58, v100, v3
	v_add_u32_e32 v60, v101, v16
	v_mov_b32_e32 v30, v27
	v_mov_b32_e32 v32, v29
	v_ashrrev_i32_e32 v63, 31, v36
	v_ashrrev_i32_e32 v65, 31, v25
	v_mad_u64_u32 v[34:35], s[26:27], v2, v25, 0
	v_mad_u64_u32 v[36:37], s[26:27], v0, v36, 0
	v_ashrrev_i32_e32 v25, 31, v40
	v_ashrrev_i32_e32 v67, 31, v38
	v_mad_u64_u32 v[38:39], s[26:27], v2, v38, 0
	v_mad_u64_u32 v[40:41], s[26:27], v0, v40, 0
	v_ashrrev_i32_e32 v69, 31, v44
	v_ashrrev_i32_e32 v71, 31, v42
	v_mad_u64_u32 v[42:43], s[26:27], v2, v42, 0
	v_mad_u64_u32 v[44:45], s[26:27], v0, v44, 0
	v_ashrrev_i32_e32 v73, 31, v48
	v_ashrrev_i32_e32 v75, 31, v46
	v_mad_u64_u32 v[46:47], s[26:27], v2, v46, 0
	v_mad_u64_u32 v[48:49], s[26:27], v0, v48, 0
	v_ashrrev_i32_e32 v77, 31, v52
	v_ashrrev_i32_e32 v79, 31, v50
	v_mad_u64_u32 v[50:51], s[26:27], v2, v50, 0
	v_mad_u64_u32 v[52:53], s[26:27], v0, v52, 0
	v_ashrrev_i32_e32 v81, 31, v56
	v_ashrrev_i32_e32 v83, 31, v54
	v_mad_u64_u32 v[54:55], s[26:27], v2, v54, 0
	v_mad_u64_u32 v[56:57], s[26:27], v0, v56, 0
	v_ashrrev_i32_e32 v85, 31, v60
	v_ashrrev_i32_e32 v102, 31, v58
	v_mad_u64_u32 v[58:59], s[26:27], v2, v58, 0
	v_mad_u64_u32 v[60:61], s[26:27], v0, v60, 0
	v_mad_u64_u32 v[30:31], s[26:27], v2, v31, v[30:31]
	v_mad_u64_u32 v[32:33], s[26:27], v0, v33, v[32:33]
	v_mov_b32_e32 v62, v35
	v_mov_b32_e32 v64, v37
	v_mov_b32_e32 v66, v39
	v_mov_b32_e32 v68, v41
	v_mov_b32_e32 v70, v43
	v_mov_b32_e32 v72, v45
	v_mov_b32_e32 v74, v47
	v_mov_b32_e32 v76, v49
	v_mov_b32_e32 v78, v51
	v_mov_b32_e32 v80, v53
	v_mov_b32_e32 v82, v55
	v_mov_b32_e32 v84, v57
	v_mov_b32_e32 v86, v59
	v_mov_b32_e32 v88, v61
	v_mov_b32_e32 v27, v30
	v_mov_b32_e32 v29, v32
	v_mad_u64_u32 v[30:31], s[26:27], v2, v65, v[62:63]
	v_mad_u64_u32 v[32:33], s[26:27], v0, v63, v[64:65]
	v_mad_u64_u32 v[62:63], s[26:27], v2, v67, v[66:67]
	v_mad_u64_u32 v[64:65], s[26:27], v0, v25, v[68:69]
	v_mad_u64_u32 v[66:67], s[26:27], v2, v71, v[70:71]
	v_mad_u64_u32 v[68:69], s[26:27], v0, v69, v[72:73]
	v_mad_u64_u32 v[70:71], s[26:27], v2, v75, v[74:75]
	v_mad_u64_u32 v[72:73], s[26:27], v0, v73, v[76:77]
	v_mad_u64_u32 v[74:75], s[26:27], v2, v79, v[78:79]
	v_mad_u64_u32 v[76:77], s[26:27], v0, v77, v[80:81]
	v_mad_u64_u32 v[78:79], s[26:27], v2, v83, v[82:83]
	v_mad_u64_u32 v[80:81], s[26:27], v0, v81, v[84:85]
	v_mad_u64_u32 v[82:83], s[26:27], v2, v102, v[86:87]
	v_mad_u64_u32 v[84:85], s[26:27], v0, v85, v[88:89]
	v_lshl_add_u64 v[28:29], v[28:29], 2, v[18:19]
	v_mov_b32_e32 v35, v30
	v_mov_b32_e32 v37, v32
	v_mov_b32_e32 v39, v62
	v_mov_b32_e32 v41, v64
	v_mov_b32_e32 v43, v66
	v_mov_b32_e32 v45, v68
	v_mov_b32_e32 v47, v70
	v_mov_b32_e32 v49, v72
	v_mov_b32_e32 v51, v74
	v_mov_b32_e32 v53, v76
	v_mov_b32_e32 v55, v78
	v_mov_b32_e32 v57, v80
	v_mov_b32_e32 v59, v82
	v_mov_b32_e32 v61, v84
	v_lshl_add_u64 v[26:27], v[26:27], 2, v[18:19]
	v_lshl_add_u64 v[30:31], v[36:37], 2, v[18:19]
	v_lshl_add_u64 v[32:33], v[34:35], 2, v[18:19]
	v_lshl_add_u64 v[34:35], v[40:41], 2, v[18:19]
	v_lshl_add_u64 v[36:37], v[38:39], 2, v[18:19]
	v_lshl_add_u64 v[38:39], v[44:45], 2, v[18:19]
	v_lshl_add_u64 v[40:41], v[42:43], 2, v[18:19]
	v_lshl_add_u64 v[42:43], v[48:49], 2, v[18:19]
	v_lshl_add_u64 v[44:45], v[46:47], 2, v[18:19]
	v_lshl_add_u64 v[46:47], v[52:53], 2, v[18:19]
	v_lshl_add_u64 v[48:49], v[50:51], 2, v[18:19]
	v_lshl_add_u64 v[50:51], v[56:57], 2, v[18:19]
	v_lshl_add_u64 v[52:53], v[54:55], 2, v[18:19]
	v_lshl_add_u64 v[54:55], v[60:61], 2, v[18:19]
	v_lshl_add_u64 v[56:57], v[58:59], 2, v[18:19]
	global_load_dword v25, v[28:29], off nt
	global_load_dword v58, v[26:27], off nt
	global_load_dword v59, v[30:31], off nt
	global_load_dword v60, v[32:33], off nt
	global_load_dword v61, v[34:35], off nt
	global_load_dword v62, v[36:37], off nt
	global_load_dword v63, v[38:39], off nt
	global_load_dword v64, v[40:41], off nt
	global_load_dword v65, v[42:43], off nt
	global_load_dword v66, v[44:45], off nt
	global_load_dword v67, v[46:47], off nt
	global_load_dword v68, v[48:49], off nt
	global_load_dword v69, v[50:51], off nt
	global_load_dword v70, v[52:53], off nt
	global_load_dword v71, v[54:55], off nt
	global_load_dword v72, v[56:57], off nt
	s_add_i32 s23, s23, 16
	s_add_i32 s22, s22, 16
	s_add_i32 s24, s24, -16
	v_mad_u64_u32 v[26:27], s[26:27], v17, s35, v[8:9]
	s_cmp_lg_u32 s24, 0
	v_mad_u64_u32 v[28:29], s[26:27], v11, s35, v[8:9]
	v_mad_u64_u32 v[30:31], s[26:27], v89, s35, v[8:9]
	v_mad_u64_u32 v[32:33], s[26:27], v87, s35, v[8:9]
	v_mad_u64_u32 v[34:35], s[26:27], v91, s35, v[8:9]
	v_mad_u64_u32 v[36:37], s[26:27], v90, s35, v[8:9]
	v_mad_u64_u32 v[38:39], s[26:27], v93, s35, v[8:9]
	v_mad_u64_u32 v[40:41], s[26:27], v92, s35, v[8:9]
	v_mad_u64_u32 v[42:43], s[26:27], v95, s35, v[8:9]
	v_mad_u64_u32 v[44:45], s[26:27], v94, s35, v[8:9]
	v_mad_u64_u32 v[46:47], s[26:27], v97, s35, v[8:9]
	v_mad_u64_u32 v[48:49], s[26:27], v96, s35, v[8:9]
	v_mad_u64_u32 v[50:51], s[26:27], v99, s35, v[8:9]
	v_mad_u64_u32 v[52:53], s[26:27], v98, s35, v[8:9]
	v_mad_u64_u32 v[54:55], s[26:27], v101, s35, v[8:9]
	v_mad_u64_u32 v[56:57], s[26:27], v100, s35, v[8:9]
	s_waitcnt vmcnt(15)
	ds_write_b32 v26, v25
	s_waitcnt vmcnt(14)
	ds_write_b32 v28, v58
	s_waitcnt vmcnt(13)
	ds_write_b32 v30, v59
	s_waitcnt vmcnt(12)
	ds_write_b32 v32, v60
	s_waitcnt vmcnt(11)
	ds_write_b32 v34, v61
	s_waitcnt vmcnt(10)
	ds_write_b32 v36, v62
	s_waitcnt vmcnt(9)
	ds_write_b32 v38, v63
	s_waitcnt vmcnt(8)
	ds_write_b32 v40, v64
	s_waitcnt vmcnt(7)
	ds_write_b32 v42, v65
	s_waitcnt vmcnt(6)
	ds_write_b32 v44, v66
	s_waitcnt vmcnt(5)
	ds_write_b32 v46, v67
	s_waitcnt vmcnt(4)
	ds_write_b32 v48, v68
	s_waitcnt vmcnt(3)
	ds_write_b32 v50, v69
	s_waitcnt vmcnt(2)
	ds_write_b32 v52, v70
	s_waitcnt vmcnt(1)
	ds_write_b32 v54, v71
	s_waitcnt vmcnt(0)
	ds_write_b32 v56, v72
	s_cbranch_scc1 .LBB0_1482
	s_waitcnt lgkmcnt(0)
	v_ashrrev_i32_e32 v17, 31, v16
	ds_read2_b32 v[18:19], v20 offset0:33 offset1:41
	ds_read2_b32 v[26:27], v20 offset1:8
	ds_read2_b32 v[28:29], v20 offset0:66 offset1:74
	ds_read2_b32 v[30:31], v20 offset0:99 offset1:107
	ds_read2_b32 v[32:33], v20 offset0:132 offset1:140
	ds_read2_b32 v[34:35], v20 offset0:165 offset1:173
	ds_read2_b32 v[36:37], v20 offset0:198 offset1:206
	ds_read2_b32 v[38:39], v20 offset0:231 offset1:239
	v_lshl_add_u64 v[2:3], v[16:17], 1, v[14:15]
	v_mov_b32_e32 v11, v7
	v_add_u32_e32 v0, v24, v9
	v_lshl_add_u64 v[2:3], v[2:3], 0, v[10:11]
	v_ashrrev_i32_e32 v11, 31, v0
	s_waitcnt lgkmcnt(6)
	v_cvt_pk_bf16_f32 v14, v26, v18
	v_mul_lo_u32 v11, v12, v11
	v_mul_lo_u32 v18, v13, v0
	v_mad_u64_u32 v[40:41], s[22:23], v12, v0, 0
	v_add3_u32 v41, v41, v11, v18
	s_waitcnt lgkmcnt(4)
	v_cvt_pk_bf16_f32 v15, v28, v30
	s_waitcnt lgkmcnt(2)
	v_cvt_pk_bf16_f32 v16, v32, v34
	s_waitcnt lgkmcnt(0)
	v_cvt_pk_bf16_f32 v17, v36, v38
	v_lshl_add_u64 v[40:41], v[40:41], 1, v[2:3]
	v_add_u32_e32 v0, v24, v21
	global_store_dwordx4 v[40:41], v[14:17], off
	v_ashrrev_i32_e32 v11, 31, v0
	v_mul_lo_u32 v11, v12, v11
	v_cvt_pk_bf16_f32 v14, v27, v19
	v_cvt_pk_bf16_f32 v15, v29, v31
	v_cvt_pk_bf16_f32 v16, v33, v35
	v_cvt_pk_bf16_f32 v17, v37, v39
	v_mul_lo_u32 v25, v13, v0
	v_mad_u64_u32 v[18:19], s[22:23], v12, v0, 0
	ds_read2_b32 v[26:27], v20 offset0:16 offset1:24
	ds_read2_b32 v[28:29], v20 offset0:49 offset1:57
	ds_read2_b32 v[30:31], v20 offset0:82 offset1:90
	ds_read2_b32 v[32:33], v20 offset0:115 offset1:123
	ds_read2_b32 v[34:35], v20 offset0:148 offset1:156
	ds_read2_b32 v[36:37], v20 offset0:181 offset1:189
	ds_read2_b32 v[38:39], v20 offset0:214 offset1:222
	ds_read2_b32 v[40:41], v20 offset0:247 offset1:255
	v_add3_u32 v19, v19, v11, v25
	v_add_u32_e32 v0, v24, v22
	v_lshl_add_u64 v[18:19], v[18:19], 1, v[2:3]
	v_ashrrev_i32_e32 v11, 31, v0
	global_store_dwordx4 v[18:19], v[14:17], off
	v_mul_lo_u32 v11, v12, v11
	v_mul_lo_u32 v25, v13, v0
	v_mad_u64_u32 v[18:19], s[22:23], v12, v0, 0
	v_add3_u32 v19, v19, v11, v25
	v_add_u32_e32 v0, v24, v23
	s_waitcnt lgkmcnt(6)
	v_cvt_pk_bf16_f32 v14, v26, v28
	s_waitcnt lgkmcnt(4)
	v_cvt_pk_bf16_f32 v15, v30, v32
	s_waitcnt lgkmcnt(2)
	v_cvt_pk_bf16_f32 v16, v34, v36
	s_waitcnt lgkmcnt(0)
	v_cvt_pk_bf16_f32 v17, v38, v40
	v_lshl_add_u64 v[18:19], v[18:19], 1, v[2:3]
	v_ashrrev_i32_e32 v11, 31, v0
	global_store_dwordx4 v[18:19], v[14:17], off
	v_mul_lo_u32 v11, v12, v11
	v_mul_lo_u32 v18, v13, v0
	v_mad_u64_u32 v[12:13], s[22:23], v12, v0, 0
	v_add3_u32 v13, v13, v11, v18
	v_cvt_pk_bf16_f32 v14, v27, v29
	v_cvt_pk_bf16_f32 v15, v31, v33
	v_cvt_pk_bf16_f32 v16, v35, v37
	v_cvt_pk_bf16_f32 v17, v39, v41
	v_lshl_add_u64 v[2:3], v[12:13], 1, v[2:3]
	global_store_dwordx4 v[2:3], v[14:17], off
	v_add_u32_e32 v5, s33, v5
	s_waitcnt lgkmcnt(0)
	v_cmp_lt_i32_e32 vcc, s56, v5
	s_or_b64 s[20:21], vcc, s[20:21]
	s_andn2_b64 exec, exec, s[20:21]
	s_cbranch_execnz .LBB0_1417

.LBB0_1490:
	s_lshl_b32 s13, s12, 1
	s_lshl_b32 s14, s11, 1
	v_or_b32_e32 v9, s13, v1
	v_or_b32_e32 v11, s14, v0
	s_add_i32 s15, s13, 4
	s_add_i32 s16, s14, 4
	s_add_i32 s17, s13, 8
	s_add_i32 s18, s14, 8
	s_add_i32 s19, s13, 12
	s_add_i32 s20, s14, 12
	s_add_i32 s21, s13, 16
	s_add_i32 s22, s14, 16
	s_add_i32 s23, s13, 20
	s_add_i32 s24, s14, 20
	s_add_i32 s25, s13, 24
	s_add_i32 s26, s14, 24
	s_add_i32 s13, s13, 28
	s_add_i32 s14, s14, 28
	v_add_u32_e32 v22, v11, v10
	v_or_b32_e32 v52, s15, v1
	v_or_b32_e32 v53, s16, v0
	v_or_b32_e32 v54, s17, v1
	v_or_b32_e32 v55, s18, v0
	v_or_b32_e32 v56, s19, v1
	v_or_b32_e32 v57, s20, v0
	v_or_b32_e32 v58, s21, v1
	v_or_b32_e32 v59, s22, v0
	v_or_b32_e32 v60, s23, v1
	v_or_b32_e32 v61, s24, v0
	v_or_b32_e32 v62, s25, v1
	v_or_b32_e32 v63, s26, v0
	v_or_b32_e32 v64, s13, v1
	v_or_b32_e32 v65, s14, v0
	v_add_u32_e32 v20, v9, v3
	v_ashrrev_i32_e32 v23, 31, v22
	v_add_u32_e32 v24, v52, v3
	v_add_u32_e32 v26, v53, v10
	v_add_u32_e32 v28, v54, v3
	v_add_u32_e32 v30, v55, v10
	v_add_u32_e32 v32, v56, v3
	v_add_u32_e32 v34, v57, v10
	v_add_u32_e32 v36, v58, v3
	v_add_u32_e32 v38, v59, v10
	v_add_u32_e32 v40, v60, v3
	v_add_u32_e32 v42, v61, v10
	v_add_u32_e32 v44, v62, v3
	v_add_u32_e32 v46, v63, v10
	v_add_u32_e32 v48, v64, v3
	v_add_u32_e32 v50, v65, v10
	v_ashrrev_i32_e32 v21, 31, v20
	v_lshlrev_b64 v[22:23], 13, v[22:23]
	v_ashrrev_i32_e32 v27, 31, v26
	v_ashrrev_i32_e32 v25, 31, v24
	v_ashrrev_i32_e32 v31, 31, v30
	v_ashrrev_i32_e32 v29, 31, v28
	v_ashrrev_i32_e32 v35, 31, v34
	v_ashrrev_i32_e32 v33, 31, v32
	v_ashrrev_i32_e32 v39, 31, v38
	v_ashrrev_i32_e32 v37, 31, v36
	v_ashrrev_i32_e32 v43, 31, v42
	v_ashrrev_i32_e32 v41, 31, v40
	v_ashrrev_i32_e32 v47, 31, v46
	v_ashrrev_i32_e32 v45, 31, v44
	v_ashrrev_i32_e32 v51, 31, v50
	v_ashrrev_i32_e32 v49, 31, v48
	v_lshlrev_b64 v[20:21], 13, v[20:21]
	v_lshl_add_u64 v[22:23], v[12:13], 0, v[22:23]
	v_lshlrev_b64 v[24:25], 13, v[24:25]
	v_lshlrev_b64 v[26:27], 13, v[26:27]
	v_lshlrev_b64 v[28:29], 13, v[28:29]
	v_lshlrev_b64 v[30:31], 13, v[30:31]
	v_lshlrev_b64 v[32:33], 13, v[32:33]
	v_lshlrev_b64 v[34:35], 13, v[34:35]
	v_lshlrev_b64 v[36:37], 13, v[36:37]
	v_lshlrev_b64 v[38:39], 13, v[38:39]
	v_lshlrev_b64 v[40:41], 13, v[40:41]
	v_lshlrev_b64 v[42:43], 13, v[42:43]
	v_lshlrev_b64 v[44:45], 13, v[44:45]
	v_lshlrev_b64 v[46:47], 13, v[46:47]
	v_lshlrev_b64 v[48:49], 13, v[48:49]
	v_lshlrev_b64 v[50:51], 13, v[50:51]
	v_lshl_add_u64 v[20:21], v[12:13], 0, v[20:21]
	v_lshl_add_u64 v[26:27], v[12:13], 0, v[26:27]
	v_lshl_add_u64 v[24:25], v[12:13], 0, v[24:25]
	v_lshl_add_u64 v[30:31], v[12:13], 0, v[30:31]
	v_lshl_add_u64 v[28:29], v[12:13], 0, v[28:29]
	v_lshl_add_u64 v[34:35], v[12:13], 0, v[34:35]
	v_lshl_add_u64 v[32:33], v[12:13], 0, v[32:33]
	v_lshl_add_u64 v[38:39], v[12:13], 0, v[38:39]
	v_lshl_add_u64 v[36:37], v[12:13], 0, v[36:37]
	v_lshl_add_u64 v[42:43], v[12:13], 0, v[42:43]
	v_lshl_add_u64 v[40:41], v[12:13], 0, v[40:41]
	v_lshl_add_u64 v[46:47], v[12:13], 0, v[46:47]
	v_lshl_add_u64 v[44:45], v[12:13], 0, v[44:45]
	v_lshl_add_u64 v[50:51], v[12:13], 0, v[50:51]
	v_lshl_add_u64 v[48:49], v[12:13], 0, v[48:49]
	global_load_dword v66, v[22:23], off nt
	global_load_dword v67, v[20:21], off nt
	global_load_dword v68, v[26:27], off nt
	global_load_dword v69, v[24:25], off nt
	global_load_dword v70, v[30:31], off nt
	global_load_dword v71, v[28:29], off nt
	global_load_dword v72, v[34:35], off nt
	global_load_dword v73, v[32:33], off nt
	global_load_dword v74, v[38:39], off nt
	global_load_dword v75, v[36:37], off nt
	global_load_dword v76, v[42:43], off nt
	global_load_dword v77, v[40:41], off nt
	global_load_dword v78, v[46:47], off nt
	global_load_dword v79, v[44:45], off nt
	global_load_dword v80, v[50:51], off nt
	global_load_dword v81, v[48:49], off nt
	s_add_i32 s11, s11, 16
	s_add_i32 s12, s12, 16
	s_add_i32 s10, s10, -16
	v_mad_u64_u32 v[20:21], s[14:15], v11, s7, v[2:3]
	s_cmp_lg_u32 s10, 0
	v_mad_u64_u32 v[22:23], s[14:15], v9, s7, v[2:3]
	v_mad_u64_u32 v[24:25], s[14:15], v53, s7, v[2:3]
	v_mad_u64_u32 v[26:27], s[14:15], v52, s7, v[2:3]
	v_mad_u64_u32 v[28:29], s[14:15], v55, s7, v[2:3]
	v_mad_u64_u32 v[30:31], s[14:15], v54, s7, v[2:3]
	v_mad_u64_u32 v[32:33], s[14:15], v57, s7, v[2:3]
	v_mad_u64_u32 v[34:35], s[14:15], v56, s7, v[2:3]
	v_mad_u64_u32 v[36:37], s[14:15], v59, s7, v[2:3]
	v_mad_u64_u32 v[38:39], s[14:15], v58, s7, v[2:3]
	v_mad_u64_u32 v[40:41], s[14:15], v61, s7, v[2:3]
	v_mad_u64_u32 v[42:43], s[14:15], v60, s7, v[2:3]
	v_mad_u64_u32 v[44:45], s[14:15], v63, s7, v[2:3]
	v_mad_u64_u32 v[46:47], s[14:15], v62, s7, v[2:3]
	v_mad_u64_u32 v[48:49], s[14:15], v65, s7, v[2:3]
	v_mad_u64_u32 v[50:51], s[14:15], v64, s7, v[2:3]
	s_waitcnt vmcnt(15)
	ds_write_b32 v20, v66
	s_waitcnt vmcnt(14)
	ds_write_b32 v22, v67
	s_waitcnt vmcnt(13)
	ds_write_b32 v24, v68
	s_waitcnt vmcnt(12)
	ds_write_b32 v26, v69
	s_waitcnt vmcnt(11)
	ds_write_b32 v28, v70
	s_waitcnt vmcnt(10)
	ds_write_b32 v30, v71
	s_waitcnt vmcnt(9)
	ds_write_b32 v32, v72
	s_waitcnt vmcnt(8)
	ds_write_b32 v34, v73
	s_waitcnt vmcnt(7)
	ds_write_b32 v36, v74
	s_waitcnt vmcnt(6)
	ds_write_b32 v38, v75
	s_waitcnt vmcnt(5)
	ds_write_b32 v40, v76
	s_waitcnt vmcnt(4)
	ds_write_b32 v42, v77
	s_waitcnt vmcnt(3)
	ds_write_b32 v44, v78
	s_waitcnt vmcnt(2)
	ds_write_b32 v46, v79
	s_waitcnt vmcnt(1)
	ds_write_b32 v48, v80
	s_waitcnt vmcnt(0)
	ds_write_b32 v50, v81
	s_cbranch_scc1 .LBB0_1490
	s_waitcnt lgkmcnt(0)
	ds_read2_b32 v[20:21], v16 offset0:33 offset1:41
	ds_read2_b32 v[22:23], v16 offset1:8
	ds_read2_b32 v[24:25], v16 offset0:66 offset1:74
	ds_read2_b32 v[26:27], v16 offset0:99 offset1:107
	ds_read2_b32 v[28:29], v16 offset0:132 offset1:140
	ds_read2_b32 v[30:31], v16 offset0:165 offset1:173
	ds_read2_b32 v[32:33], v16 offset0:198 offset1:206
	ds_read2_b32 v[34:35], v16 offset0:231 offset1:239
	v_ashrrev_i32_e32 v11, 31, v10
	v_lshl_add_u64 v[36:37], v[10:11], 1, v[6:7]
	v_or_b32_e32 v3, v8, v15
	s_waitcnt lgkmcnt(6)
	v_cvt_pk_bf16_f32 v10, v22, v20
	s_waitcnt lgkmcnt(4)
	v_cvt_pk_bf16_f32 v11, v24, v26
	s_waitcnt lgkmcnt(2)
	v_cvt_pk_bf16_f32 v12, v28, v30
	s_waitcnt lgkmcnt(0)
	v_cvt_pk_bf16_f32 v13, v32, v34
	v_mad_i64_i32 v[38:39], s[10:11], v3, s8, v[36:37]
	global_store_dwordx4 v[38:39], v[10:13], off
	v_or_b32_e32 v3, v8, v17
	v_add_u32_e32 v14, s6, v14
	v_cvt_pk_bf16_f32 v10, v23, v21
	v_cvt_pk_bf16_f32 v11, v25, v27
	v_cvt_pk_bf16_f32 v12, v29, v31
	v_cvt_pk_bf16_f32 v13, v33, v35
	ds_read2_b32 v[22:23], v16 offset0:49 offset1:57
	ds_read2_b32 v[24:25], v16 offset0:16 offset1:24
	ds_read2_b32 v[26:27], v16 offset0:82 offset1:90
	ds_read2_b32 v[28:29], v16 offset0:115 offset1:123
	ds_read2_b32 v[30:31], v16 offset0:148 offset1:156
	ds_read2_b32 v[32:33], v16 offset0:181 offset1:189
	ds_read2_b32 v[34:35], v16 offset0:214 offset1:222
	ds_read2_b32 v[38:39], v16 offset0:247 offset1:255
	v_mad_i64_i32 v[20:21], s[10:11], v3, s8, v[36:37]
	v_or_b32_e32 v3, v8, v18
	global_store_dwordx4 v[20:21], v[10:13], off
	v_mad_i64_i32 v[20:21], s[10:11], v3, s8, v[36:37]
	s_waitcnt lgkmcnt(6)
	v_cvt_pk_bf16_f32 v10, v24, v22
	s_waitcnt lgkmcnt(4)
	v_cvt_pk_bf16_f32 v11, v26, v28
	s_waitcnt lgkmcnt(2)
	v_cvt_pk_bf16_f32 v12, v30, v32
	s_waitcnt lgkmcnt(0)
	v_cvt_pk_bf16_f32 v13, v34, v38
	v_or_b32_e32 v3, v8, v19
	global_store_dwordx4 v[20:21], v[10:13], off
	v_mad_i64_i32 v[8:9], s[10:11], v3, s8, v[36:37]
	s_nop 0
	v_cvt_pk_bf16_f32 v10, v25, v23
	v_cvt_pk_bf16_f32 v11, v27, v29
	v_cvt_pk_bf16_f32 v12, v31, v33
	v_cvt_pk_bf16_f32 v13, v35, v39
	global_store_dwordx4 v[8:9], v[10:13], off
	s_waitcnt lgkmcnt(0)
	v_cmp_lt_i32_e32 vcc, s9, v14
	s_or_b64 s[4:5], vcc, s[4:5]
	s_andn2_b64 exec, exec, s[4:5]
	s_cbranch_execnz .LBB0_1489
